# FFN-up sample-tile epilogue: the eight groups of carried-in conv-state loads software-pipelined by one group into spare registers (replaces the up-front cache warm-up)
# speedup vs baseline: 1.0566x; 1.0032x over previous
;     __device__ __forceinline__ f32x4 conv4s(const f32x4 c4, const f32x4 pv, int t, const f32x4 w0, const f32x4 w1, const f32x4 w2, const f32x4 bsv) const {
;         f32x4 p1, p2;
; #pragma unroll
;         for (int e = 0; e < 4; ++e) { p1[e] = dpp_f<0x111>(0.f, c4[e]); p2[e] = dpp_f<0x112>(0.f, c4[e]); const float q1 = dpp_f<0x101>(0.f, pv[e]);
;             p1[e] = t == 0 ? q1 : p1[e]; p2[e] = t < 2 ? pv[e] : p2[e]; }
;         f32x4 uu = bsv + w2 * c4 + w1 * p1 + w0 * p2;
;         asm volatile("" : "+v"(uu));
;         return uu;
;     }
;     __device__ __forceinline__ void sample(f32x4 (&acc)[2][2][4][2], const Unit& u, int row0t, int wr, int wc, int fr, int fq) const {
;     ...
;         const unsigned stoff = (unsigned)((sql * 2 + (t & 1)) * DFF2 + ca) * 4u;
; #pragma unroll
;         for (int n = 0; n < 2; ++n) {
;             const unsigned cso = (unsigned)((ca + 4 * n) * 4);
;             const f32x4 w0 = *(const f32x4*)((const char*)cw + cso), w1 = *(const f32x4*)((const char*)(cw + DFF2) + cso), w2 = *(const f32x4*)((const char*)(cw + 2 * DFF2) + cso), bsv = *(const f32x4*)((const char*)cb + cso);
; #pragma unroll
;             for (int ai = 0; ai < 2; ++ai) {
; #pragma unroll
;                 for (int mp = 0; mp < 4; mp += 4) {
;                     f32x4 pv[4];
; #pragma unroll
;                     for (int k = 0; k < 4; ++k) { pv[k] = (f32x4){0.f, 0.f, 0.f, 0.f}; if (t < 2) pv[k] = *(const f32x4*)((const char*)st + stoff + (unsigned)(((16 * ai + 2 * (mp + k)) * 2 * DFF2 + 4 * n) * 4)); }
; #pragma unroll
;                     for (int k = 0; k < 4; ++k) acc[ai][0][mp + k][n] = conv4s(acc[ai][0][mp + k][n], pv[k], t, w0, w1, w2, bsv);
;                     __builtin_amdgcn_sched_barrier(0);
;                 }
;             }
.LBB0_1312:
	s_or_b64 exec, exec, s[0:1]
	v_readlane_b32 s4, v245, 3
	v_readlane_b32 s8, v245, 7
	v_readlane_b32 s9, v245, 8
	v_readlane_b32 s10, v245, 9
	v_readlane_b32 s11, v245, 10
	v_readlane_b32 s12, v245, 11
	v_readlane_b32 s13, v245, 12
	v_readlane_b32 s14, v245, 13
	v_readlane_b32 s15, v245, 14
	s_mov_b64 s[8:9], s[12:13]
	s_lshl_b64 s[0:1], s[50:51], 2
	s_mov_b64 s[10:11], s[14:15]
	s_add_u32 s2, s10, s0
	s_addc_u32 s3, s11, s1
	s_add_u32 s0, s96, 0x5800
	s_addc_u32 s1, s97, 0
	v_lshlrev_b32_e32 v176, 2, v175
	s_add_u32 s8, s96, 0xb000
	s_addc_u32 s9, s97, 0
	global_load_dwordx4 v[152:155], v176, s[0:1]
	global_load_dwordx4 v[156:159], v176, s[8:9]
	global_load_dwordx4 v[24:27], v176, s[96:97]
	global_load_dwordx4 v[160:163], v176, s[66:67]
	v_and_or_b32 v18, v222, 1, v28
	s_movk_i32 s4, 0x1600
	v_mul_lo_u32 v18, v18, s4
	v_readlane_b32 s5, v245, 4
	v_add_lshl_u32 v18, v175, v18, 2
	v_readlane_b32 s6, v245, 5
	v_readlane_b32 s7, v245, 6
	v_cmp_gt_u32_e64 s[4:5], 2, v108
	v_lshl_add_u64 v[172:173], s[2:3], 0, v[18:19]
	v_mov_b32_e32 v36, 0
	v_mov_b32_e32 v100, 0
	v_mov_b32_e32 v101, 0
	v_mov_b32_e32 v102, 0
	v_mov_b32_e32 v103, 0
	v_readlane_b32 s16, v245, 15
	v_readlane_b32 s17, v245, 16
	v_readlane_b32 s18, v245, 17
	v_readlane_b32 s19, v245, 18
	v_mov_b32_e32 v178, 0
	v_mov_b32_e32 v179, 0
	v_mov_b32_e32 v180, 0
	v_mov_b32_e32 v181, 0
	v_mov_b32_e32 v182, 0
	v_mov_b32_e32 v183, 0
	v_mov_b32_e32 v184, 0
	v_mov_b32_e32 v185, 0
	v_mov_b32_e32 v186, 0
	v_mov_b32_e32 v187, 0
	v_mov_b32_e32 v188, 0
	v_mov_b32_e32 v189, 0
	v_mov_b32_e32 v190, 0
	v_mov_b32_e32 v191, 0
	v_mov_b32_e32 v192, 0
	v_mov_b32_e32 v193, 0
	s_and_saveexec_b64 s[100:101], s[4:5]
	s_cbranch_execz .Lspp_0
	global_load_dwordx4 v[178:181], v[172:173], off
	s_mov_b64 s[98:99], 0x16000
	v_lshl_add_u64 v[194:195], v[172:173], 0, s[98:99]
	global_load_dwordx4 v[182:185], v[194:195], off
	s_mov_b64 s[98:99], 0x2c000
	v_lshl_add_u64 v[194:195], v[172:173], 0, s[98:99]
	global_load_dwordx4 v[186:189], v[194:195], off
	s_mov_b64 s[98:99], 0x42000
	v_lshl_add_u64 v[194:195], v[172:173], 0, s[98:99]
	global_load_dwordx4 v[190:193], v[194:195], off
.Lspp_0:
	s_or_b64 exec, exec, s[100:101]
	s_nop 4
	v_mov_b32_e32 v37, 0
	v_mov_b32_e32 v38, 0
	v_mov_b32_e32 v39, 0
	v_mov_b32_e32 v28, 0
	v_mov_b32_e32 v40, 0
	v_mov_b32_e32 v41, 0
	v_mov_b32_e32 v42, 0
	v_mov_b32_e32 v43, 0
	v_mov_b32_e32 v29, 0
	v_mov_b32_e32 v30, 0
	v_mov_b32_e32 v31, 0
	v_mov_b32_e32 v18, v19
	v_mov_b32_e32 v109, v19
	v_mov_b32_e32 v110, v19
	v_mov_b32_dpp v18, v168 row_shr:1 row_mask:0xf bank_mask:0xf
	v_mov_b32_dpp v109, v168 row_shr:2 row_mask:0xf bank_mask:0xf
	s_waitcnt vmcnt(0)
	v_mov_b32_e32 v204, 0
	v_mov_b32_e32 v205, 0
	v_mov_b32_e32 v206, 0
	v_mov_b32_e32 v207, 0
	v_mov_b32_e32 v208, 0
	v_mov_b32_e32 v209, 0
	v_mov_b32_e32 v210, 0
	v_mov_b32_e32 v211, 0
	v_mov_b32_e32 v212, 0
	v_mov_b32_e32 v213, 0
	v_mov_b32_e32 v214, 0
	v_mov_b32_e32 v215, 0
	v_mov_b32_e32 v216, 0
	v_mov_b32_e32 v217, 0
	v_mov_b32_e32 v218, 0
	v_mov_b32_e32 v219, 0
	s_and_saveexec_b64 s[100:101], s[4:5]
	s_cbranch_execz .Lspp_1
	s_mov_b64 s[98:99], 0xb0000
	v_lshl_add_u64 v[194:195], v[172:173], 0, s[98:99]
	global_load_dwordx4 v[204:207], v[194:195], off
	s_mov_b64 s[98:99], 0xc6000
	v_lshl_add_u64 v[194:195], v[172:173], 0, s[98:99]
	global_load_dwordx4 v[208:211], v[194:195], off
	s_mov_b64 s[98:99], 0xdc000
	v_lshl_add_u64 v[194:195], v[172:173], 0, s[98:99]
	global_load_dwordx4 v[212:215], v[194:195], off
	s_mov_b64 s[98:99], 0xf2000
	v_lshl_add_u64 v[194:195], v[172:173], 0, s[98:99]
	global_load_dwordx4 v[216:219], v[194:195], off
.Lspp_1:
	s_or_b64 exec, exec, s[100:101]
	s_nop 4
	v_mov_b32_dpp v110, v178 row_shl:1 row_mask:0xf bank_mask:0xf
	v_cmp_eq_u32_e64 s[6:7], 0, v108
	v_cndmask_b32_e64 v100, v109, v178, s[4:5]
	v_mov_b32_e32 v109, v19
	v_cndmask_b32_e64 v108, v18, v110, s[6:7]
	v_mov_b32_e32 v18, v19
	v_mov_b32_e32 v110, v19
	v_mov_b32_dpp v109, v179 row_shl:1 row_mask:0xf bank_mask:0xf
	v_mov_b32_dpp v18, v169 row_shr:1 row_mask:0xf bank_mask:0xf
	v_mov_b32_dpp v110, v169 row_shr:2 row_mask:0xf bank_mask:0xf
	v_cndmask_b32_e64 v109, v18, v109, s[6:7]
	v_cndmask_b32_e64 v101, v110, v179, s[4:5]
	v_mov_b32_e32 v18, v19
	v_mov_b32_e32 v111, v19
	v_mov_b32_e32 v110, v19
	v_mov_b32_dpp v18, v170 row_shr:1 row_mask:0xf bank_mask:0xf
	v_mov_b32_dpp v111, v170 row_shr:2 row_mask:0xf bank_mask:0xf
	v_mov_b32_dpp v110, v180 row_shl:1 row_mask:0xf bank_mask:0xf
	v_cndmask_b32_e64 v110, v18, v110, s[6:7]
	v_cndmask_b32_e64 v102, v111, v180, s[4:5]
	v_mov_b32_e32 v18, v19
	v_mov_b32_e32 v112, v19
	v_mov_b32_e32 v111, v19
	v_mov_b32_dpp v18, v171 row_shr:1 row_mask:0xf bank_mask:0xf
	v_mov_b32_dpp v112, v171 row_shr:2 row_mask:0xf bank_mask:0xf
	v_mov_b32_dpp v111, v181 row_shl:1 row_mask:0xf bank_mask:0xf
	v_pk_fma_f32 v[114:115], v[168:169], v[156:157], v[160:161]
	v_cndmask_b32_e64 v111, v18, v111, s[6:7]
	v_cndmask_b32_e64 v103, v112, v181, s[4:5]
	v_pk_fma_f32 v[112:113], v[170:171], v[158:159], v[162:163]
	v_pk_fma_f32 v[108:109], v[152:153], v[108:109], v[114:115]
	v_pk_fma_f32 v[110:111], v[154:155], v[110:111], v[112:113]
	v_pk_fma_f32 v[112:113], v[24:25], v[100:101], v[108:109]
	v_mov_b32_e32 v18, v19
	v_mov_b32_e32 v101, v19
	v_mov_b32_e32 v100, v19
	v_mov_b32_dpp v18, v164 row_shr:1 row_mask:0xf bank_mask:0xf
	v_mov_b32_dpp v101, v164 row_shr:2 row_mask:0xf bank_mask:0xf
	v_mov_b32_dpp v100, v182 row_shl:1 row_mask:0xf bank_mask:0xf
	v_pk_fma_f32 v[114:115], v[26:27], v[102:103], v[110:111]
	v_cndmask_b32_e64 v100, v18, v100, s[6:7]
	v_cndmask_b32_e64 v36, v101, v182, s[4:5]
	v_mov_b32_e32 v18, v19
	v_mov_b32_e32 v102, v19
;     __device__ __forceinline__ f32x4 conv4s(const f32x4 c4, const f32x4 pv, int t, const f32x4 w0, const f32x4 w1, const f32x4 w2, const f32x4 bsv) const {
;         f32x4 p1, p2;
; #pragma unroll
;         for (int e = 0; e < 4; ++e) { p1[e] = dpp_f<0x111>(0.f, c4[e]); p2[e] = dpp_f<0x112>(0.f, c4[e]); const float q1 = dpp_f<0x101>(0.f, pv[e]);
;             p1[e] = t == 0 ? q1 : p1[e]; p2[e] = t < 2 ? pv[e] : p2[e]; }
;         f32x4 uu = bsv + w2 * c4 + w1 * p1 + w0 * p2;
;         asm volatile("" : "+v"(uu));
;         return uu;
;     }
;     __device__ __forceinline__ void sample(f32x4 (&acc)[2][2][4][2], const Unit& u, int row0t, int wr, int wc, int fr, int fq) const {
;     ...
;         const unsigned stoff = (unsigned)((sql * 2 + (t & 1)) * DFF2 + ca) * 4u;
; #pragma unroll
;         for (int n = 0; n < 2; ++n) {
;             const unsigned cso = (unsigned)((ca + 4 * n) * 4);
;             const f32x4 w0 = *(const f32x4*)((const char*)cw + cso), w1 = *(const f32x4*)((const char*)(cw + DFF2) + cso), w2 = *(const f32x4*)((const char*)(cw + 2 * DFF2) + cso), bsv = *(const f32x4*)((const char*)cb + cso);
; #pragma unroll
;             for (int ai = 0; ai < 2; ++ai) {
; #pragma unroll
;                 for (int mp = 0; mp < 4; mp += 4) {
;                     f32x4 pv[4];
; #pragma unroll
;                     for (int k = 0; k < 4; ++k) { pv[k] = (f32x4){0.f, 0.f, 0.f, 0.f}; if (t < 2) pv[k] = *(const f32x4*)((const char*)st + stoff + (unsigned)(((16 * ai + 2 * (mp + k)) * 2 * DFF2 + 4 * n) * 4)); }
; #pragma unroll
;                     for (int k = 0; k < 4; ++k) acc[ai][0][mp + k][n] = conv4s(acc[ai][0][mp + k][n], pv[k], t, w0, w1, w2, bsv);
;                     __builtin_amdgcn_sched_barrier(0);
;                 }
;             }
	v_mov_b32_e32 v101, v19
	v_mov_b32_dpp v18, v165 row_shr:1 row_mask:0xf bank_mask:0xf
	v_mov_b32_dpp v102, v165 row_shr:2 row_mask:0xf bank_mask:0xf
	v_mov_b32_dpp v101, v183 row_shl:1 row_mask:0xf bank_mask:0xf
	v_cndmask_b32_e64 v101, v18, v101, s[6:7]
	v_cndmask_b32_e64 v37, v102, v183, s[4:5]
	v_mov_b32_e32 v18, v19
	v_mov_b32_e32 v103, v19
	v_mov_b32_e32 v102, v19
	v_mov_b32_dpp v18, v166 row_shr:1 row_mask:0xf bank_mask:0xf
	v_mov_b32_dpp v103, v166 row_shr:2 row_mask:0xf bank_mask:0xf
	v_mov_b32_dpp v102, v184 row_shl:1 row_mask:0xf bank_mask:0xf
	v_cndmask_b32_e64 v102, v18, v102, s[6:7]
	v_cndmask_b32_e64 v38, v103, v184, s[4:5]
	v_mov_b32_e32 v18, v19
	v_mov_b32_e32 v108, v19
	v_mov_b32_e32 v103, v19
	v_mov_b32_dpp v18, v167 row_shr:1 row_mask:0xf bank_mask:0xf
	v_mov_b32_dpp v108, v167 row_shr:2 row_mask:0xf bank_mask:0xf
	v_mov_b32_dpp v103, v185 row_shl:1 row_mask:0xf bank_mask:0xf
	v_pk_fma_f32 v[110:111], v[164:165], v[156:157], v[160:161]
	v_cndmask_b32_e64 v103, v18, v103, s[6:7]
	v_cndmask_b32_e64 v39, v108, v185, s[4:5]
	v_pk_fma_f32 v[108:109], v[166:167], v[158:159], v[162:163]
	v_pk_fma_f32 v[100:101], v[152:153], v[100:101], v[110:111]
	v_pk_fma_f32 v[102:103], v[154:155], v[102:103], v[108:109]
	v_pk_fma_f32 v[108:109], v[24:25], v[36:37], v[100:101]
	v_mov_b32_e32 v18, v19
	v_mov_b32_e32 v37, v19
	v_mov_b32_e32 v36, v19
	v_mov_b32_dpp v18, v104 row_shr:1 row_mask:0xf bank_mask:0xf
	v_mov_b32_dpp v37, v104 row_shr:2 row_mask:0xf bank_mask:0xf
	v_mov_b32_dpp v36, v186 row_shl:1 row_mask:0xf bank_mask:0xf
	v_pk_fma_f32 v[110:111], v[26:27], v[38:39], v[102:103]
	v_cndmask_b32_e64 v36, v18, v36, s[6:7]
	v_cndmask_b32_e64 v38, v37, v186, s[4:5]
	v_mov_b32_e32 v18, v19
	v_mov_b32_e32 v39, v19
	v_mov_b32_e32 v37, v19
	v_mov_b32_dpp v18, v105 row_shr:1 row_mask:0xf bank_mask:0xf
	v_mov_b32_dpp v39, v105 row_shr:2 row_mask:0xf bank_mask:0xf
	v_mov_b32_dpp v37, v187 row_shl:1 row_mask:0xf bank_mask:0xf
	v_cndmask_b32_e64 v37, v18, v37, s[6:7]
	v_cndmask_b32_e64 v39, v39, v187, s[4:5]
	v_mov_b32_e32 v18, v19
	v_mov_b32_e32 v41, v19
	v_mov_b32_e32 v40, v19
	v_mov_b32_dpp v18, v106 row_shr:1 row_mask:0xf bank_mask:0xf
	v_mov_b32_dpp v41, v106 row_shr:2 row_mask:0xf bank_mask:0xf
	v_mov_b32_dpp v40, v188 row_shl:1 row_mask:0xf bank_mask:0xf
	v_cndmask_b32_e64 v40, v18, v40, s[6:7]
	v_cndmask_b32_e64 v42, v41, v188, s[4:5]
	v_mov_b32_e32 v18, v19
	v_mov_b32_e32 v41, v19
	v_pk_fma_f32 v[102:103], v[104:105], v[156:157], v[160:161]
	v_mov_b32_dpp v18, v107 row_shr:1 row_mask:0xf bank_mask:0xf
	v_mov_b32_dpp v41, v189 row_shl:1 row_mask:0xf bank_mask:0xf
	v_pk_fma_f32 v[36:37], v[152:153], v[36:37], v[102:103]
	v_cndmask_b32_e64 v41, v18, v41, s[6:7]
	v_pk_fma_f32 v[104:105], v[24:25], v[38:39], v[36:37]
	v_mov_b32_e32 v18, v19
	v_mov_b32_e32 v37, v19
	v_mov_b32_e32 v36, v19
	v_mov_b32_dpp v18, v136 row_shr:1 row_mask:0xf bank_mask:0xf
	v_mov_b32_dpp v37, v136 row_shr:2 row_mask:0xf bank_mask:0xf
	v_mov_b32_dpp v36, v190 row_shl:1 row_mask:0xf bank_mask:0xf
	v_mov_b32_e32 v100, v19
	v_cndmask_b32_e64 v36, v18, v36, s[6:7]
	v_cndmask_b32_e64 v28, v37, v190, s[4:5]
	v_mov_b32_e32 v18, v19
	v_mov_b32_e32 v38, v19
	v_mov_b32_e32 v37, v19
	v_mov_b32_dpp v100, v107 row_shr:2 row_mask:0xf bank_mask:0xf
	v_mov_b32_dpp v18, v137 row_shr:1 row_mask:0xf bank_mask:0xf
	v_mov_b32_dpp v38, v137 row_shr:2 row_mask:0xf bank_mask:0xf
	v_mov_b32_dpp v37, v191 row_shl:1 row_mask:0xf bank_mask:0xf
	v_cndmask_b32_e64 v43, v100, v189, s[4:5]
	v_pk_fma_f32 v[100:101], v[106:107], v[158:159], v[162:163]
	v_cndmask_b32_e64 v37, v18, v37, s[6:7]
	v_cndmask_b32_e64 v29, v38, v191, s[4:5]
	v_mov_b32_e32 v18, v19
	v_mov_b32_e32 v39, v19
	v_mov_b32_e32 v38, v19
	v_pk_fma_f32 v[40:41], v[154:155], v[40:41], v[100:101]
	v_mov_b32_dpp v18, v138 row_shr:1 row_mask:0xf bank_mask:0xf
	v_mov_b32_dpp v39, v138 row_shr:2 row_mask:0xf bank_mask:0xf
	v_mov_b32_dpp v38, v192 row_shl:1 row_mask:0xf bank_mask:0xf
	v_pk_fma_f32 v[106:107], v[26:27], v[42:43], v[40:41]
	v_cndmask_b32_e64 v38, v18, v38, s[6:7]
	v_cndmask_b32_e64 v30, v39, v192, s[4:5]
	v_mov_b32_e32 v18, v19
	v_mov_b32_e32 v40, v19
	v_mov_b32_e32 v39, v19
	v_mov_b32_dpp v18, v139 row_shr:1 row_mask:0xf bank_mask:0xf
	v_mov_b32_dpp v40, v139 row_shr:2 row_mask:0xf bank_mask:0xf
	v_mov_b32_dpp v39, v193 row_shl:1 row_mask:0xf bank_mask:0xf
	v_cndmask_b32_e64 v39, v18, v39, s[6:7]
	v_cndmask_b32_e64 v31, v40, v193, s[4:5]
	v_pk_fma_f32 v[40:41], v[138:139], v[158:159], v[162:163]
	v_pk_fma_f32 v[42:43], v[136:137], v[156:157], v[160:161]
	v_pk_fma_f32 v[38:39], v[154:155], v[38:39], v[40:41]
	v_pk_fma_f32 v[36:37], v[152:153], v[36:37], v[42:43]
	v_pk_fma_f32 v[102:103], v[26:27], v[30:31], v[38:39]
	v_pk_fma_f32 v[100:101], v[24:25], v[28:29], v[36:37]
	s_nop 0
	v_mov_b32_e32 v28, 0
	v_mov_b32_e32 v36, 0
	v_mov_b32_e32 v37, 0
	v_mov_b32_e32 v38, 0
	v_mov_b32_e32 v39, 0
	v_mov_b32_e32 v29, 0
	v_mov_b32_e32 v30, 0
	v_mov_b32_e32 v31, 0
	v_mov_b32_e32 v136, 0
	v_mov_b32_e32 v164, 0
	v_mov_b32_e32 v165, 0
	v_mov_b32_e32 v166, 0
	v_mov_b32_e32 v167, 0
	v_mov_b32_e32 v137, 0
	v_mov_b32_e32 v138, 0
	v_mov_b32_e32 v139, 0
	v_mov_b32_e32 v18, v19
	v_mov_b32_e32 v41, v19
	v_mov_b32_e32 v40, v19
	v_mov_b32_dpp v18, v148 row_shr:1 row_mask:0xf bank_mask:0xf
	v_mov_b32_dpp v41, v148 row_shr:2 row_mask:0xf bank_mask:0xf
	s_waitcnt vmcnt(0)
	v_mov_b32_e32 v178, 0
	v_mov_b32_e32 v179, 0
	v_mov_b32_e32 v180, 0
	v_mov_b32_e32 v181, 0
	v_mov_b32_e32 v182, 0
	v_mov_b32_e32 v183, 0
	v_mov_b32_e32 v184, 0
	v_mov_b32_e32 v185, 0
	v_mov_b32_e32 v186, 0
	v_mov_b32_e32 v187, 0
	v_mov_b32_e32 v188, 0
	v_mov_b32_e32 v189, 0
	v_mov_b32_e32 v190, 0
	v_mov_b32_e32 v191, 0
	v_mov_b32_e32 v192, 0
	v_mov_b32_e32 v193, 0
	s_and_saveexec_b64 s[100:101], s[4:5]
	s_cbranch_execz .Lspp_2
	s_mov_b64 s[98:99], 0x10
	v_lshl_add_u64 v[194:195], v[172:173], 0, s[98:99]
	global_load_dwordx4 v[178:181], v[194:195], off
	s_mov_b64 s[98:99], 0x16010
	v_lshl_add_u64 v[194:195], v[172:173], 0, s[98:99]
	global_load_dwordx4 v[182:185], v[194:195], off
	s_mov_b64 s[98:99], 0x2c010
	v_lshl_add_u64 v[194:195], v[172:173], 0, s[98:99]
	global_load_dwordx4 v[186:189], v[194:195], off
	s_mov_b64 s[98:99], 0x42010
	v_lshl_add_u64 v[194:195], v[172:173], 0, s[98:99]
	global_load_dwordx4 v[190:193], v[194:195], off
;     __device__ __forceinline__ f32x4 conv4s(const f32x4 c4, const f32x4 pv, int t, const f32x4 w0, const f32x4 w1, const f32x4 w2, const f32x4 bsv) const {
;         f32x4 p1, p2;
; #pragma unroll
;         for (int e = 0; e < 4; ++e) { p1[e] = dpp_f<0x111>(0.f, c4[e]); p2[e] = dpp_f<0x112>(0.f, c4[e]); const float q1 = dpp_f<0x101>(0.f, pv[e]);
;             p1[e] = t == 0 ? q1 : p1[e]; p2[e] = t < 2 ? pv[e] : p2[e]; }
;         f32x4 uu = bsv + w2 * c4 + w1 * p1 + w0 * p2;
;         asm volatile("" : "+v"(uu));
;         return uu;
;     }
;     __device__ __forceinline__ void sample(f32x4 (&acc)[2][2][4][2], const Unit& u, int row0t, int wr, int wc, int fr, int fq) const {
;     ...
;         const unsigned stoff = (unsigned)((sql * 2 + (t & 1)) * DFF2 + ca) * 4u;
; #pragma unroll
;         for (int n = 0; n < 2; ++n) {
;             const unsigned cso = (unsigned)((ca + 4 * n) * 4);
;             const f32x4 w0 = *(const f32x4*)((const char*)cw + cso), w1 = *(const f32x4*)((const char*)(cw + DFF2) + cso), w2 = *(const f32x4*)((const char*)(cw + 2 * DFF2) + cso), bsv = *(const f32x4*)((const char*)cb + cso);
; #pragma unroll
;             for (int ai = 0; ai < 2; ++ai) {
; #pragma unroll
;                 for (int mp = 0; mp < 4; mp += 4) {
;                     f32x4 pv[4];
; #pragma unroll
;                     for (int k = 0; k < 4; ++k) { pv[k] = (f32x4){0.f, 0.f, 0.f, 0.f}; if (t < 2) pv[k] = *(const f32x4*)((const char*)st + stoff + (unsigned)(((16 * ai + 2 * (mp + k)) * 2 * DFF2 + 4 * n) * 4)); }
; #pragma unroll
;                     for (int k = 0; k < 4; ++k) acc[ai][0][mp + k][n] = conv4s(acc[ai][0][mp + k][n], pv[k], t, w0, w1, w2, bsv);
;                     __builtin_amdgcn_sched_barrier(0);
;                 }
;             }
.Lspp_2:
	s_or_b64 exec, exec, s[100:101]
	s_nop 4
	v_mov_b32_dpp v40, v204 row_shl:1 row_mask:0xf bank_mask:0xf
	v_cndmask_b32_e64 v40, v18, v40, s[6:7]
	v_cndmask_b32_e64 v36, v41, v204, s[4:5]
	v_mov_b32_e32 v18, v19
	v_mov_b32_e32 v42, v19
	v_mov_b32_e32 v41, v19
	v_mov_b32_dpp v18, v149 row_shr:1 row_mask:0xf bank_mask:0xf
	v_mov_b32_dpp v42, v149 row_shr:2 row_mask:0xf bank_mask:0xf
	v_mov_b32_dpp v41, v205 row_shl:1 row_mask:0xf bank_mask:0xf
	v_cndmask_b32_e64 v41, v18, v41, s[6:7]
	v_cndmask_b32_e64 v37, v42, v205, s[4:5]
	v_mov_b32_e32 v18, v19
	v_mov_b32_e32 v43, v19
	v_mov_b32_e32 v42, v19
	v_mov_b32_dpp v18, v150 row_shr:1 row_mask:0xf bank_mask:0xf
	v_mov_b32_dpp v43, v150 row_shr:2 row_mask:0xf bank_mask:0xf
	v_mov_b32_dpp v42, v206 row_shl:1 row_mask:0xf bank_mask:0xf
	v_cndmask_b32_e64 v42, v18, v42, s[6:7]
	v_cndmask_b32_e64 v38, v43, v206, s[4:5]
	v_mov_b32_e32 v18, v19
	v_mov_b32_e32 v43, v19
	v_pk_fma_f32 v[148:149], v[148:149], v[156:157], v[160:161]
	v_mov_b32_dpp v18, v151 row_shr:1 row_mask:0xf bank_mask:0xf
	v_mov_b32_e32 v168, v19
	v_mov_b32_dpp v43, v207 row_shl:1 row_mask:0xf bank_mask:0xf
	v_pk_fma_f32 v[40:41], v[152:153], v[40:41], v[148:149]
	v_mov_b32_dpp v168, v151 row_shr:2 row_mask:0xf bank_mask:0xf
	v_cndmask_b32_e64 v43, v18, v43, s[6:7]
	v_pk_fma_f32 v[150:151], v[150:151], v[158:159], v[162:163]
	v_pk_fma_f32 v[40:41], v[24:25], v[36:37], v[40:41]
	v_mov_b32_e32 v18, v19
	v_mov_b32_e32 v37, v19
	v_mov_b32_e32 v36, v19
	v_cndmask_b32_e64 v39, v168, v207, s[4:5]
	v_pk_fma_f32 v[42:43], v[154:155], v[42:43], v[150:151]
	v_mov_b32_dpp v18, v144 row_shr:1 row_mask:0xf bank_mask:0xf
	v_mov_b32_dpp v37, v144 row_shr:2 row_mask:0xf bank_mask:0xf
	v_mov_b32_dpp v36, v208 row_shl:1 row_mask:0xf bank_mask:0xf
	v_pk_fma_f32 v[42:43], v[26:27], v[38:39], v[42:43]
	v_cndmask_b32_e64 v36, v18, v36, s[6:7]
	v_cndmask_b32_e64 v28, v37, v208, s[4:5]
	v_mov_b32_e32 v18, v19
	v_mov_b32_e32 v38, v19
	v_mov_b32_e32 v37, v19
	v_mov_b32_dpp v18, v145 row_shr:1 row_mask:0xf bank_mask:0xf
	v_mov_b32_dpp v38, v145 row_shr:2 row_mask:0xf bank_mask:0xf
	v_mov_b32_dpp v37, v209 row_shl:1 row_mask:0xf bank_mask:0xf
	v_cndmask_b32_e64 v37, v18, v37, s[6:7]
	v_cndmask_b32_e64 v29, v38, v209, s[4:5]
	v_mov_b32_e32 v18, v19
	v_mov_b32_e32 v39, v19
	v_mov_b32_e32 v38, v19
	v_mov_b32_dpp v18, v146 row_shr:1 row_mask:0xf bank_mask:0xf
	v_mov_b32_dpp v39, v146 row_shr:2 row_mask:0xf bank_mask:0xf
	v_mov_b32_dpp v38, v210 row_shl:1 row_mask:0xf bank_mask:0xf
	v_cndmask_b32_e64 v38, v18, v38, s[6:7]
	v_cndmask_b32_e64 v30, v39, v210, s[4:5]
	v_mov_b32_e32 v18, v19
	v_mov_b32_e32 v39, v19
	v_pk_fma_f32 v[144:145], v[144:145], v[156:157], v[160:161]
	v_mov_b32_dpp v18, v147 row_shr:1 row_mask:0xf bank_mask:0xf
	v_mov_b32_e32 v148, v19
	v_mov_b32_dpp v39, v211 row_shl:1 row_mask:0xf bank_mask:0xf
	v_pk_fma_f32 v[36:37], v[152:153], v[36:37], v[144:145]
	v_mov_b32_dpp v148, v147 row_shr:2 row_mask:0xf bank_mask:0xf
	v_cndmask_b32_e64 v39, v18, v39, s[6:7]
	v_pk_fma_f32 v[146:147], v[146:147], v[158:159], v[162:163]
	v_pk_fma_f32 v[36:37], v[24:25], v[28:29], v[36:37]
	v_mov_b32_e32 v18, v19
	v_mov_b32_e32 v29, v19
	v_mov_b32_e32 v28, v19
	v_cndmask_b32_e64 v31, v148, v211, s[4:5]
	v_pk_fma_f32 v[38:39], v[154:155], v[38:39], v[146:147]
	v_mov_b32_dpp v18, v140 row_shr:1 row_mask:0xf bank_mask:0xf
	v_mov_b32_dpp v29, v140 row_shr:2 row_mask:0xf bank_mask:0xf
	v_mov_b32_dpp v28, v212 row_shl:1 row_mask:0xf bank_mask:0xf
	v_pk_fma_f32 v[38:39], v[26:27], v[30:31], v[38:39]
	v_cndmask_b32_e64 v28, v18, v28, s[6:7]
	v_cndmask_b32_e64 v144, v29, v212, s[4:5]
	v_mov_b32_e32 v18, v19
	v_mov_b32_e32 v30, v19
	v_mov_b32_e32 v29, v19
	v_mov_b32_dpp v18, v141 row_shr:1 row_mask:0xf bank_mask:0xf
	v_mov_b32_dpp v30, v141 row_shr:2 row_mask:0xf bank_mask:0xf
	v_mov_b32_dpp v29, v213 row_shl:1 row_mask:0xf bank_mask:0xf
	v_cndmask_b32_e64 v29, v18, v29, s[6:7]
	v_cndmask_b32_e64 v145, v30, v213, s[4:5]
	v_mov_b32_e32 v18, v19
	v_mov_b32_e32 v31, v19
	v_mov_b32_e32 v30, v19
	v_mov_b32_dpp v18, v142 row_shr:1 row_mask:0xf bank_mask:0xf
	v_mov_b32_dpp v31, v142 row_shr:2 row_mask:0xf bank_mask:0xf
	v_mov_b32_dpp v30, v214 row_shl:1 row_mask:0xf bank_mask:0xf
	v_cndmask_b32_e64 v30, v18, v30, s[6:7]
	v_cndmask_b32_e64 v146, v31, v214, s[4:5]
	v_mov_b32_e32 v18, v19
	v_mov_b32_e32 v31, v19
	v_pk_fma_f32 v[140:141], v[140:141], v[156:157], v[160:161]
	v_mov_b32_dpp v18, v143 row_shr:1 row_mask:0xf bank_mask:0xf
	v_mov_b32_dpp v31, v215 row_shl:1 row_mask:0xf bank_mask:0xf
	v_mov_b32_e32 v147, v19
	v_cndmask_b32_e64 v31, v18, v31, s[6:7]
	v_pk_fma_f32 v[28:29], v[152:153], v[28:29], v[140:141]
	v_mov_b32_e32 v18, v19
	v_mov_b32_e32 v141, v19
	v_mov_b32_e32 v140, v19
	v_mov_b32_dpp v147, v143 row_shr:2 row_mask:0xf bank_mask:0xf
	v_pk_fma_f32 v[142:143], v[142:143], v[158:159], v[162:163]
	v_mov_b32_dpp v18, v128 row_shr:1 row_mask:0xf bank_mask:0xf
	v_mov_b32_dpp v141, v128 row_shr:2 row_mask:0xf bank_mask:0xf
	v_mov_b32_dpp v140, v216 row_shl:1 row_mask:0xf bank_mask:0xf
	v_pk_fma_f32 v[30:31], v[154:155], v[30:31], v[142:143]
	v_cndmask_b32_e64 v140, v18, v140, s[6:7]
	v_cndmask_b32_e64 v136, v141, v216, s[4:5]
	v_mov_b32_e32 v18, v19
	v_mov_b32_e32 v142, v19
	v_mov_b32_e32 v141, v19
	v_mov_b32_dpp v18, v129 row_shr:1 row_mask:0xf bank_mask:0xf
	v_mov_b32_dpp v142, v129 row_shr:2 row_mask:0xf bank_mask:0xf
	v_mov_b32_dpp v141, v217 row_shl:1 row_mask:0xf bank_mask:0xf
	v_cndmask_b32_e64 v141, v18, v141, s[6:7]
	v_cndmask_b32_e64 v137, v142, v217, s[4:5]
	v_mov_b32_e32 v18, v19
	v_mov_b32_e32 v143, v19
	v_mov_b32_e32 v142, v19
	v_mov_b32_dpp v18, v130 row_shr:1 row_mask:0xf bank_mask:0xf
;     __device__ __forceinline__ f32x4 conv4s(const f32x4 c4, const f32x4 pv, int t, const f32x4 w0, const f32x4 w1, const f32x4 w2, const f32x4 bsv) const {
;         f32x4 p1, p2;
; #pragma unroll
;         for (int e = 0; e < 4; ++e) { p1[e] = dpp_f<0x111>(0.f, c4[e]); p2[e] = dpp_f<0x112>(0.f, c4[e]); const float q1 = dpp_f<0x101>(0.f, pv[e]);
;             p1[e] = t == 0 ? q1 : p1[e]; p2[e] = t < 2 ? pv[e] : p2[e]; }
;         f32x4 uu = bsv + w2 * c4 + w1 * p1 + w0 * p2;
;         asm volatile("" : "+v"(uu));
;         return uu;
;     }
;     __device__ __forceinline__ void sample(f32x4 (&acc)[2][2][4][2], const Unit& u, int row0t, int wr, int wc, int fr, int fq) const {
;     ...
;         const unsigned stoff = (unsigned)((sql * 2 + (t & 1)) * DFF2 + ca) * 4u;
; #pragma unroll
;         for (int n = 0; n < 2; ++n) {
;             const unsigned cso = (unsigned)((ca + 4 * n) * 4);
;             const f32x4 w0 = *(const f32x4*)((const char*)cw + cso), w1 = *(const f32x4*)((const char*)(cw + DFF2) + cso), w2 = *(const f32x4*)((const char*)(cw + 2 * DFF2) + cso), bsv = *(const f32x4*)((const char*)cb + cso);
; #pragma unroll
;             for (int ai = 0; ai < 2; ++ai) {
; #pragma unroll
;                 for (int mp = 0; mp < 4; mp += 4) {
;                     f32x4 pv[4];
; #pragma unroll
;                     for (int k = 0; k < 4; ++k) { pv[k] = (f32x4){0.f, 0.f, 0.f, 0.f}; if (t < 2) pv[k] = *(const f32x4*)((const char*)st + stoff + (unsigned)(((16 * ai + 2 * (mp + k)) * 2 * DFF2 + 4 * n) * 4)); }
; #pragma unroll
;                     for (int k = 0; k < 4; ++k) acc[ai][0][mp + k][n] = conv4s(acc[ai][0][mp + k][n], pv[k], t, w0, w1, w2, bsv);
;                     __builtin_amdgcn_sched_barrier(0);
;                 }
;             }
	v_mov_b32_dpp v143, v130 row_shr:2 row_mask:0xf bank_mask:0xf
	v_mov_b32_dpp v142, v218 row_shl:1 row_mask:0xf bank_mask:0xf
	v_cndmask_b32_e64 v142, v18, v142, s[6:7]
	v_cndmask_b32_e64 v138, v143, v218, s[4:5]
	v_mov_b32_e32 v18, v19
	v_mov_b32_e32 v143, v19
	v_pk_fma_f32 v[28:29], v[24:25], v[144:145], v[28:29]
	v_mov_b32_dpp v18, v131 row_shr:1 row_mask:0xf bank_mask:0xf
	v_mov_b32_e32 v144, v19
	v_mov_b32_dpp v143, v219 row_shl:1 row_mask:0xf bank_mask:0xf
	v_cndmask_b32_e64 v143, v18, v143, s[6:7]
	v_mov_b32_dpp v144, v131 row_shr:2 row_mask:0xf bank_mask:0xf
	v_pk_fma_f32 v[130:131], v[130:131], v[158:159], v[162:163]
	v_pk_fma_f32 v[128:129], v[128:129], v[156:157], v[160:161]
	v_cndmask_b32_e64 v147, v147, v215, s[4:5]
	v_cndmask_b32_e64 v139, v144, v219, s[4:5]
	v_pk_fma_f32 v[130:131], v[154:155], v[142:143], v[130:131]
	v_pk_fma_f32 v[128:129], v[152:153], v[140:141], v[128:129]
	v_pk_fma_f32 v[30:31], v[26:27], v[146:147], v[30:31]
	v_pk_fma_f32 v[26:27], v[26:27], v[138:139], v[130:131]
	v_pk_fma_f32 v[24:25], v[24:25], v[136:137], v[128:129]
	s_nop 0
	v_add_u32_e32 v18, 16, v176
	global_load_dwordx4 v[140:143], v18, s[0:1]
	global_load_dwordx4 v[144:147], v18, s[8:9]
	global_load_dwordx4 v[136:139], v18, s[96:97]
	global_load_dwordx4 v[148:151], v18, s[66:67]
	v_mov_b32_e32 v156, 0
	v_mov_b32_e32 v128, 0
	v_mov_b32_e32 v129, 0
	v_mov_b32_e32 v130, 0
	v_mov_b32_e32 v131, 0
	v_mov_b32_e32 v157, 0
	v_mov_b32_e32 v158, 0
	v_mov_b32_e32 v159, 0
	v_mov_b32_e32 v152, 0
	v_mov_b32_e32 v160, 0
	v_mov_b32_e32 v161, 0
	v_mov_b32_e32 v162, 0
	v_mov_b32_e32 v163, 0
	v_mov_b32_e32 v153, 0
	v_mov_b32_e32 v154, 0
	v_mov_b32_e32 v155, 0
	v_mov_b32_e32 v18, v19
	v_mov_b32_e32 v165, v19
	v_mov_b32_e32 v164, v19
	v_mov_b32_dpp v18, v124 row_shr:1 row_mask:0xf bank_mask:0xf
	v_mov_b32_dpp v165, v124 row_shr:2 row_mask:0xf bank_mask:0xf
	s_waitcnt vmcnt(0)
	v_mov_b32_e32 v204, 0
	v_mov_b32_e32 v205, 0
	v_mov_b32_e32 v206, 0
	v_mov_b32_e32 v207, 0
	v_mov_b32_e32 v208, 0
	v_mov_b32_e32 v209, 0
	v_mov_b32_e32 v210, 0
	v_mov_b32_e32 v211, 0
	v_mov_b32_e32 v212, 0
	v_mov_b32_e32 v213, 0
	v_mov_b32_e32 v214, 0
	v_mov_b32_e32 v215, 0
	v_mov_b32_e32 v216, 0
	v_mov_b32_e32 v217, 0
	v_mov_b32_e32 v218, 0
	v_mov_b32_e32 v219, 0
	s_and_saveexec_b64 s[100:101], s[4:5]
	s_cbranch_execz .Lspp_3
	s_mov_b64 s[98:99], 0xb0010
	v_lshl_add_u64 v[194:195], v[172:173], 0, s[98:99]
	global_load_dwordx4 v[204:207], v[194:195], off
	s_mov_b64 s[98:99], 0xc6010
	v_lshl_add_u64 v[194:195], v[172:173], 0, s[98:99]
	global_load_dwordx4 v[208:211], v[194:195], off
	s_mov_b64 s[98:99], 0xdc010
	v_lshl_add_u64 v[194:195], v[172:173], 0, s[98:99]
	global_load_dwordx4 v[212:215], v[194:195], off
	s_mov_b64 s[98:99], 0xf2010
	v_lshl_add_u64 v[194:195], v[172:173], 0, s[98:99]
	global_load_dwordx4 v[216:219], v[194:195], off
.Lspp_3:
	s_or_b64 exec, exec, s[100:101]
	s_nop 4
	v_mov_b32_dpp v164, v178 row_shl:1 row_mask:0xf bank_mask:0xf
	v_cndmask_b32_e64 v164, v18, v164, s[6:7]
	v_cndmask_b32_e64 v128, v165, v178, s[4:5]
	v_mov_b32_e32 v18, v19
	v_mov_b32_e32 v166, v19
	v_mov_b32_e32 v165, v19
	v_mov_b32_dpp v18, v125 row_shr:1 row_mask:0xf bank_mask:0xf
	v_mov_b32_dpp v166, v125 row_shr:2 row_mask:0xf bank_mask:0xf
	v_mov_b32_dpp v165, v179 row_shl:1 row_mask:0xf bank_mask:0xf
	v_cndmask_b32_e64 v165, v18, v165, s[6:7]
	v_cndmask_b32_e64 v129, v166, v179, s[4:5]
	v_mov_b32_e32 v18, v19
	v_mov_b32_e32 v167, v19
	v_mov_b32_e32 v166, v19
	v_mov_b32_dpp v18, v126 row_shr:1 row_mask:0xf bank_mask:0xf
	v_mov_b32_dpp v167, v126 row_shr:2 row_mask:0xf bank_mask:0xf
	v_mov_b32_dpp v166, v180 row_shl:1 row_mask:0xf bank_mask:0xf
	v_cndmask_b32_e64 v166, v18, v166, s[6:7]
	v_cndmask_b32_e64 v130, v167, v180, s[4:5]
	v_mov_b32_e32 v18, v19
	v_mov_b32_e32 v167, v19
	v_pk_fma_f32 v[124:125], v[124:125], v[144:145], v[148:149]
	v_mov_b32_dpp v18, v127 row_shr:1 row_mask:0xf bank_mask:0xf
	v_mov_b32_e32 v168, v19
	v_mov_b32_dpp v167, v181 row_shl:1 row_mask:0xf bank_mask:0xf
	v_pk_fma_f32 v[124:125], v[140:141], v[164:165], v[124:125]
	v_mov_b32_dpp v168, v127 row_shr:2 row_mask:0xf bank_mask:0xf
	v_cndmask_b32_e64 v167, v18, v167, s[6:7]
	v_pk_fma_f32 v[126:127], v[126:127], v[146:147], v[150:151]
	v_pk_fma_f32 v[128:129], v[136:137], v[128:129], v[124:125]
	v_mov_b32_e32 v18, v19
	v_mov_b32_e32 v125, v19
	v_mov_b32_e32 v124, v19
	v_cndmask_b32_e64 v131, v168, v181, s[4:5]
	v_pk_fma_f32 v[126:127], v[142:143], v[166:167], v[126:127]
	v_mov_b32_dpp v18, v120 row_shr:1 row_mask:0xf bank_mask:0xf
	v_mov_b32_dpp v125, v120 row_shr:2 row_mask:0xf bank_mask:0xf
	v_mov_b32_dpp v124, v182 row_shl:1 row_mask:0xf bank_mask:0xf
	v_pk_fma_f32 v[130:131], v[138:139], v[130:131], v[126:127]
	v_cndmask_b32_e64 v124, v18, v124, s[6:7]
	v_cndmask_b32_e64 v156, v125, v182, s[4:5]
	v_mov_b32_e32 v18, v19
	v_mov_b32_e32 v126, v19
	v_mov_b32_e32 v125, v19
	v_mov_b32_dpp v18, v121 row_shr:1 row_mask:0xf bank_mask:0xf
	v_mov_b32_dpp v126, v121 row_shr:2 row_mask:0xf bank_mask:0xf
	v_mov_b32_dpp v125, v183 row_shl:1 row_mask:0xf bank_mask:0xf
	v_cndmask_b32_e64 v125, v18, v125, s[6:7]
	v_cndmask_b32_e64 v157, v126, v183, s[4:5]
	v_mov_b32_e32 v18, v19
	v_mov_b32_e32 v127, v19
	v_mov_b32_e32 v126, v19
	v_mov_b32_dpp v18, v122 row_shr:1 row_mask:0xf bank_mask:0xf
	v_mov_b32_dpp v127, v122 row_shr:2 row_mask:0xf bank_mask:0xf
	v_mov_b32_dpp v126, v184 row_shl:1 row_mask:0xf bank_mask:0xf
	v_cndmask_b32_e64 v126, v18, v126, s[6:7]
	v_cndmask_b32_e64 v158, v127, v184, s[4:5]
	v_mov_b32_e32 v18, v19
	v_mov_b32_e32 v127, v19
	v_pk_fma_f32 v[120:121], v[120:121], v[144:145], v[148:149]
	v_mov_b32_dpp v18, v123 row_shr:1 row_mask:0xf bank_mask:0xf
;     __device__ __forceinline__ f32x4 conv4s(const f32x4 c4, const f32x4 pv, int t, const f32x4 w0, const f32x4 w1, const f32x4 w2, const f32x4 bsv) const {
;         f32x4 p1, p2;
; #pragma unroll
;         for (int e = 0; e < 4; ++e) { p1[e] = dpp_f<0x111>(0.f, c4[e]); p2[e] = dpp_f<0x112>(0.f, c4[e]); const float q1 = dpp_f<0x101>(0.f, pv[e]);
;             p1[e] = t == 0 ? q1 : p1[e]; p2[e] = t < 2 ? pv[e] : p2[e]; }
;         f32x4 uu = bsv + w2 * c4 + w1 * p1 + w0 * p2;
;         asm volatile("" : "+v"(uu));
;         return uu;
;     }
;     __device__ __forceinline__ void sample(f32x4 (&acc)[2][2][4][2], const Unit& u, int row0t, int wr, int wc, int fr, int fq) const {
;     ...
;         const unsigned stoff = (unsigned)((sql * 2 + (t & 1)) * DFF2 + ca) * 4u;
; #pragma unroll
;         for (int n = 0; n < 2; ++n) {
;             const unsigned cso = (unsigned)((ca + 4 * n) * 4);
;             const f32x4 w0 = *(const f32x4*)((const char*)cw + cso), w1 = *(const f32x4*)((const char*)(cw + DFF2) + cso), w2 = *(const f32x4*)((const char*)(cw + 2 * DFF2) + cso), bsv = *(const f32x4*)((const char*)cb + cso);
; #pragma unroll
;             for (int ai = 0; ai < 2; ++ai) {
; #pragma unroll
;                 for (int mp = 0; mp < 4; mp += 4) {
;                     f32x4 pv[4];
; #pragma unroll
;                     for (int k = 0; k < 4; ++k) { pv[k] = (f32x4){0.f, 0.f, 0.f, 0.f}; if (t < 2) pv[k] = *(const f32x4*)((const char*)st + stoff + (unsigned)(((16 * ai + 2 * (mp + k)) * 2 * DFF2 + 4 * n) * 4)); }
; #pragma unroll
;                     for (int k = 0; k < 4; ++k) acc[ai][0][mp + k][n] = conv4s(acc[ai][0][mp + k][n], pv[k], t, w0, w1, w2, bsv);
;                     __builtin_amdgcn_sched_barrier(0);
;                 }
;             }
	v_mov_b32_e32 v164, v19
	v_mov_b32_dpp v127, v185 row_shl:1 row_mask:0xf bank_mask:0xf
	v_pk_fma_f32 v[120:121], v[140:141], v[124:125], v[120:121]
	v_mov_b32_dpp v164, v123 row_shr:2 row_mask:0xf bank_mask:0xf
	v_cndmask_b32_e64 v127, v18, v127, s[6:7]
	v_pk_fma_f32 v[122:123], v[122:123], v[146:147], v[150:151]
	v_pk_fma_f32 v[124:125], v[136:137], v[156:157], v[120:121]
	v_mov_b32_e32 v18, v19
	v_mov_b32_e32 v121, v19
	v_mov_b32_e32 v120, v19
	v_cndmask_b32_e64 v159, v164, v185, s[4:5]
	v_pk_fma_f32 v[122:123], v[142:143], v[126:127], v[122:123]
	v_mov_b32_dpp v18, v116 row_shr:1 row_mask:0xf bank_mask:0xf
	v_mov_b32_dpp v121, v116 row_shr:2 row_mask:0xf bank_mask:0xf
	v_mov_b32_dpp v120, v186 row_shl:1 row_mask:0xf bank_mask:0xf
	v_pk_fma_f32 v[126:127], v[138:139], v[158:159], v[122:123]
	v_cndmask_b32_e64 v120, v18, v120, s[6:7]
	v_cndmask_b32_e64 v156, v121, v186, s[4:5]
	v_mov_b32_e32 v18, v19
	v_mov_b32_e32 v122, v19
	v_mov_b32_e32 v121, v19
	v_mov_b32_dpp v18, v117 row_shr:1 row_mask:0xf bank_mask:0xf
	v_mov_b32_dpp v122, v117 row_shr:2 row_mask:0xf bank_mask:0xf
	v_mov_b32_dpp v121, v187 row_shl:1 row_mask:0xf bank_mask:0xf
	v_cndmask_b32_e64 v121, v18, v121, s[6:7]
	v_cndmask_b32_e64 v157, v122, v187, s[4:5]
	v_mov_b32_e32 v18, v19
	v_mov_b32_e32 v123, v19
	v_mov_b32_e32 v122, v19
	v_mov_b32_dpp v18, v118 row_shr:1 row_mask:0xf bank_mask:0xf
	v_mov_b32_dpp v123, v118 row_shr:2 row_mask:0xf bank_mask:0xf
	v_mov_b32_dpp v122, v188 row_shl:1 row_mask:0xf bank_mask:0xf
	v_cndmask_b32_e64 v122, v18, v122, s[6:7]
	v_cndmask_b32_e64 v158, v123, v188, s[4:5]
	v_mov_b32_e32 v18, v19
	v_mov_b32_e32 v123, v19
	v_pk_fma_f32 v[116:117], v[116:117], v[144:145], v[148:149]
	v_mov_b32_dpp v18, v119 row_shr:1 row_mask:0xf bank_mask:0xf
	v_mov_b32_e32 v159, v19
	v_mov_b32_dpp v123, v189 row_shl:1 row_mask:0xf bank_mask:0xf
	v_pk_fma_f32 v[116:117], v[140:141], v[120:121], v[116:117]
	v_mov_b32_dpp v159, v119 row_shr:2 row_mask:0xf bank_mask:0xf
	v_cndmask_b32_e64 v123, v18, v123, s[6:7]
	v_pk_fma_f32 v[118:119], v[118:119], v[146:147], v[150:151]
	v_pk_fma_f32 v[120:121], v[136:137], v[156:157], v[116:117]
	v_mov_b32_e32 v18, v19
	v_mov_b32_e32 v117, v19
	v_mov_b32_e32 v116, v19
	v_cndmask_b32_e64 v159, v159, v189, s[4:5]
	v_pk_fma_f32 v[118:119], v[142:143], v[122:123], v[118:119]
	v_mov_b32_dpp v18, v72 row_shr:1 row_mask:0xf bank_mask:0xf
	v_mov_b32_dpp v117, v72 row_shr:2 row_mask:0xf bank_mask:0xf
	v_mov_b32_dpp v116, v190 row_shl:1 row_mask:0xf bank_mask:0xf
	v_pk_fma_f32 v[122:123], v[138:139], v[158:159], v[118:119]
	v_cndmask_b32_e64 v116, v18, v116, s[6:7]
	v_cndmask_b32_e64 v152, v117, v190, s[4:5]
	v_mov_b32_e32 v18, v19
	v_mov_b32_e32 v118, v19
	v_mov_b32_e32 v117, v19
	v_mov_b32_dpp v18, v73 row_shr:1 row_mask:0xf bank_mask:0xf
	v_mov_b32_dpp v118, v73 row_shr:2 row_mask:0xf bank_mask:0xf
	v_mov_b32_dpp v117, v191 row_shl:1 row_mask:0xf bank_mask:0xf
	v_cndmask_b32_e64 v117, v18, v117, s[6:7]
	v_cndmask_b32_e64 v153, v118, v191, s[4:5]
	v_mov_b32_e32 v18, v19
	v_mov_b32_e32 v119, v19
	v_mov_b32_e32 v118, v19
	v_mov_b32_dpp v18, v74 row_shr:1 row_mask:0xf bank_mask:0xf
	v_mov_b32_dpp v119, v74 row_shr:2 row_mask:0xf bank_mask:0xf
	v_mov_b32_dpp v118, v192 row_shl:1 row_mask:0xf bank_mask:0xf
	v_cndmask_b32_e64 v118, v18, v118, s[6:7]
	v_cndmask_b32_e64 v154, v119, v192, s[4:5]
	v_mov_b32_e32 v18, v19
	v_mov_b32_e32 v119, v19
	v_mov_b32_e32 v156, v19
	v_mov_b32_dpp v18, v75 row_shr:1 row_mask:0xf bank_mask:0xf
	v_mov_b32_dpp v119, v193 row_shl:1 row_mask:0xf bank_mask:0xf
	v_mov_b32_dpp v156, v75 row_shr:2 row_mask:0xf bank_mask:0xf
	v_cndmask_b32_e64 v119, v18, v119, s[6:7]
	v_pk_fma_f32 v[74:75], v[74:75], v[146:147], v[150:151]
	v_pk_fma_f32 v[72:73], v[72:73], v[144:145], v[148:149]
	v_cndmask_b32_e64 v155, v156, v193, s[4:5]
	v_pk_fma_f32 v[74:75], v[142:143], v[118:119], v[74:75]
	v_pk_fma_f32 v[72:73], v[140:141], v[116:117], v[72:73]
	v_pk_fma_f32 v[118:119], v[138:139], v[154:155], v[74:75]
	v_pk_fma_f32 v[116:117], v[136:137], v[152:153], v[72:73]
	s_nop 0
	v_mov_b32_e32 v156, 0
	v_mov_b32_e32 v72, 0
	v_mov_b32_e32 v73, 0
	v_mov_b32_e32 v74, 0
	v_mov_b32_e32 v75, 0
	v_mov_b32_e32 v157, 0
	v_mov_b32_e32 v158, 0
	v_mov_b32_e32 v159, 0
	v_mov_b32_e32 v152, 0
	v_mov_b32_e32 v160, 0
	v_mov_b32_e32 v161, 0
	v_mov_b32_e32 v162, 0
	v_mov_b32_e32 v163, 0
	v_mov_b32_e32 v153, 0
	v_mov_b32_e32 v154, 0
	v_mov_b32_e32 v155, 0
	v_mov_b32_e32 v18, v19
	v_mov_b32_e32 v165, v19
	v_mov_b32_e32 v164, v19
	v_mov_b32_dpp v18, v132 row_shr:1 row_mask:0xf bank_mask:0xf
	v_mov_b32_dpp v165, v132 row_shr:2 row_mask:0xf bank_mask:0xf
	s_waitcnt vmcnt(0)
	v_mov_b32_e32 v178, 0
	v_mov_b32_e32 v179, 0
	v_mov_b32_e32 v180, 0
	v_mov_b32_e32 v181, 0
	v_mov_b32_e32 v182, 0
	v_mov_b32_e32 v183, 0
	v_mov_b32_e32 v184, 0
	v_mov_b32_e32 v185, 0
	v_mov_b32_e32 v186, 0
	v_mov_b32_e32 v187, 0
	v_mov_b32_e32 v188, 0
	v_mov_b32_e32 v189, 0
	v_mov_b32_e32 v190, 0
	v_mov_b32_e32 v191, 0
	v_mov_b32_e32 v192, 0
	v_mov_b32_e32 v193, 0
	s_and_saveexec_b64 s[100:101], s[4:5]
	s_cbranch_execz .Lspp_4
	s_mov_b64 s[98:99], 0x2c00
	v_lshl_add_u64 v[194:195], v[172:173], 0, s[98:99]
	global_load_dwordx4 v[178:181], v[194:195], off
	s_mov_b64 s[98:99], 0x18c00
	v_lshl_add_u64 v[194:195], v[172:173], 0, s[98:99]
	global_load_dwordx4 v[182:185], v[194:195], off
	s_mov_b64 s[98:99], 0x2ec00
	v_lshl_add_u64 v[194:195], v[172:173], 0, s[98:99]
	global_load_dwordx4 v[186:189], v[194:195], off
	s_mov_b64 s[98:99], 0x44c00
	v_lshl_add_u64 v[194:195], v[172:173], 0, s[98:99]
	global_load_dwordx4 v[190:193], v[194:195], off
;     __device__ __forceinline__ f32x4 conv4s(const f32x4 c4, const f32x4 pv, int t, const f32x4 w0, const f32x4 w1, const f32x4 w2, const f32x4 bsv) const {
;         f32x4 p1, p2;
; #pragma unroll
;         for (int e = 0; e < 4; ++e) { p1[e] = dpp_f<0x111>(0.f, c4[e]); p2[e] = dpp_f<0x112>(0.f, c4[e]); const float q1 = dpp_f<0x101>(0.f, pv[e]);
;             p1[e] = t == 0 ? q1 : p1[e]; p2[e] = t < 2 ? pv[e] : p2[e]; }
;         f32x4 uu = bsv + w2 * c4 + w1 * p1 + w0 * p2;
;         asm volatile("" : "+v"(uu));
;         return uu;
;     }
;     __device__ __forceinline__ void sample(f32x4 (&acc)[2][2][4][2], const Unit& u, int row0t, int wr, int wc, int fr, int fq) const {
;     ...
;         const unsigned stoff = (unsigned)((sql * 2 + (t & 1)) * DFF2 + ca) * 4u;
; #pragma unroll
;         for (int n = 0; n < 2; ++n) {
;             const unsigned cso = (unsigned)((ca + 4 * n) * 4);
;             const f32x4 w0 = *(const f32x4*)((const char*)cw + cso), w1 = *(const f32x4*)((const char*)(cw + DFF2) + cso), w2 = *(const f32x4*)((const char*)(cw + 2 * DFF2) + cso), bsv = *(const f32x4*)((const char*)cb + cso);
; #pragma unroll
;             for (int ai = 0; ai < 2; ++ai) {
; #pragma unroll
;                 for (int mp = 0; mp < 4; mp += 4) {
;                     f32x4 pv[4];
; #pragma unroll
;                     for (int k = 0; k < 4; ++k) { pv[k] = (f32x4){0.f, 0.f, 0.f, 0.f}; if (t < 2) pv[k] = *(const f32x4*)((const char*)st + stoff + (unsigned)(((16 * ai + 2 * (mp + k)) * 2 * DFF2 + 4 * n) * 4)); }
; #pragma unroll
;                     for (int k = 0; k < 4; ++k) acc[ai][0][mp + k][n] = conv4s(acc[ai][0][mp + k][n], pv[k], t, w0, w1, w2, bsv);
;                     __builtin_amdgcn_sched_barrier(0);
;                 }
;             }
.Lspp_4:
	s_or_b64 exec, exec, s[100:101]
	s_nop 4
	v_mov_b32_dpp v164, v204 row_shl:1 row_mask:0xf bank_mask:0xf
	v_cndmask_b32_e64 v164, v18, v164, s[6:7]
	v_cndmask_b32_e64 v72, v165, v204, s[4:5]
	v_mov_b32_e32 v18, v19
	v_mov_b32_e32 v166, v19
	v_mov_b32_e32 v165, v19
	v_mov_b32_dpp v18, v133 row_shr:1 row_mask:0xf bank_mask:0xf
	v_mov_b32_dpp v166, v133 row_shr:2 row_mask:0xf bank_mask:0xf
	v_mov_b32_dpp v165, v205 row_shl:1 row_mask:0xf bank_mask:0xf
	v_cndmask_b32_e64 v165, v18, v165, s[6:7]
	v_cndmask_b32_e64 v73, v166, v205, s[4:5]
	v_mov_b32_e32 v18, v19
	v_mov_b32_e32 v167, v19
	v_mov_b32_e32 v166, v19
	v_mov_b32_dpp v18, v134 row_shr:1 row_mask:0xf bank_mask:0xf
	v_mov_b32_dpp v167, v134 row_shr:2 row_mask:0xf bank_mask:0xf
	v_mov_b32_dpp v166, v206 row_shl:1 row_mask:0xf bank_mask:0xf
	v_cndmask_b32_e64 v166, v18, v166, s[6:7]
	v_cndmask_b32_e64 v74, v167, v206, s[4:5]
	v_mov_b32_e32 v18, v19
	v_mov_b32_e32 v167, v19
	v_pk_fma_f32 v[132:133], v[132:133], v[144:145], v[148:149]
	v_mov_b32_dpp v18, v135 row_shr:1 row_mask:0xf bank_mask:0xf
	v_mov_b32_e32 v168, v19
	v_mov_b32_dpp v167, v207 row_shl:1 row_mask:0xf bank_mask:0xf
	v_pk_fma_f32 v[132:133], v[140:141], v[164:165], v[132:133]
	v_mov_b32_dpp v168, v135 row_shr:2 row_mask:0xf bank_mask:0xf
	v_cndmask_b32_e64 v167, v18, v167, s[6:7]
	v_pk_fma_f32 v[134:135], v[134:135], v[146:147], v[150:151]
	v_pk_fma_f32 v[72:73], v[136:137], v[72:73], v[132:133]
	v_mov_b32_e32 v18, v19
	v_mov_b32_e32 v133, v19
	v_mov_b32_e32 v132, v19
	v_cndmask_b32_e64 v75, v168, v207, s[4:5]
	v_pk_fma_f32 v[134:135], v[142:143], v[166:167], v[134:135]
	v_mov_b32_dpp v18, v76 row_shr:1 row_mask:0xf bank_mask:0xf
	v_mov_b32_dpp v133, v76 row_shr:2 row_mask:0xf bank_mask:0xf
	v_mov_b32_dpp v132, v208 row_shl:1 row_mask:0xf bank_mask:0xf
	v_pk_fma_f32 v[74:75], v[138:139], v[74:75], v[134:135]
	v_cndmask_b32_e64 v132, v18, v132, s[6:7]
	v_cndmask_b32_e64 v134, v133, v208, s[4:5]
	v_mov_b32_e32 v18, v19
	v_mov_b32_e32 v135, v19
	v_mov_b32_e32 v133, v19
	v_mov_b32_dpp v18, v77 row_shr:1 row_mask:0xf bank_mask:0xf
	v_mov_b32_dpp v135, v77 row_shr:2 row_mask:0xf bank_mask:0xf
	v_mov_b32_dpp v133, v209 row_shl:1 row_mask:0xf bank_mask:0xf
	v_cndmask_b32_e64 v133, v18, v133, s[6:7]
	v_cndmask_b32_e64 v135, v135, v209, s[4:5]
	v_mov_b32_e32 v18, v19
	v_mov_b32_e32 v157, v19
	v_mov_b32_e32 v156, v19
	v_mov_b32_dpp v18, v78 row_shr:1 row_mask:0xf bank_mask:0xf
	v_mov_b32_dpp v157, v78 row_shr:2 row_mask:0xf bank_mask:0xf
	v_mov_b32_dpp v156, v210 row_shl:1 row_mask:0xf bank_mask:0xf
	v_cndmask_b32_e64 v156, v18, v156, s[6:7]
	v_cndmask_b32_e64 v158, v157, v210, s[4:5]
	v_mov_b32_e32 v18, v19
	v_mov_b32_e32 v157, v19
	v_pk_fma_f32 v[76:77], v[76:77], v[144:145], v[148:149]
	v_mov_b32_dpp v18, v79 row_shr:1 row_mask:0xf bank_mask:0xf
	v_mov_b32_dpp v157, v211 row_shl:1 row_mask:0xf bank_mask:0xf
	v_cndmask_b32_e64 v157, v18, v157, s[6:7]
	v_pk_fma_f32 v[76:77], v[140:141], v[132:133], v[76:77]
	v_mov_b32_e32 v18, v19
	v_mov_b32_e32 v133, v19
	v_mov_b32_e32 v132, v19
	v_mov_b32_dpp v18, v80 row_shr:1 row_mask:0xf bank_mask:0xf
	v_mov_b32_dpp v133, v80 row_shr:2 row_mask:0xf bank_mask:0xf
	v_mov_b32_dpp v132, v212 row_shl:1 row_mask:0xf bank_mask:0xf
	v_mov_b32_e32 v164, v19
	v_pk_fma_f32 v[76:77], v[136:137], v[134:135], v[76:77]
	v_cndmask_b32_e64 v132, v18, v132, s[6:7]
	v_cndmask_b32_e64 v134, v133, v212, s[4:5]
	v_mov_b32_e32 v18, v19
	v_mov_b32_e32 v133, v19
	v_mov_b32_dpp v164, v79 row_shr:2 row_mask:0xf bank_mask:0xf
	v_pk_fma_f32 v[78:79], v[78:79], v[146:147], v[150:151]
	v_mov_b32_dpp v18, v81 row_shr:1 row_mask:0xf bank_mask:0xf
	v_mov_b32_dpp v133, v213 row_shl:1 row_mask:0xf bank_mask:0xf
	v_pk_fma_f32 v[78:79], v[142:143], v[156:157], v[78:79]
	v_cndmask_b32_e64 v133, v18, v133, s[6:7]
	v_mov_b32_e32 v18, v19
	v_mov_b32_e32 v157, v19
	v_mov_b32_e32 v156, v19
	v_cndmask_b32_e64 v159, v164, v211, s[4:5]
	v_mov_b32_dpp v18, v82 row_shr:1 row_mask:0xf bank_mask:0xf
	v_mov_b32_dpp v157, v82 row_shr:2 row_mask:0xf bank_mask:0xf
	v_mov_b32_dpp v156, v214 row_shl:1 row_mask:0xf bank_mask:0xf
	v_pk_fma_f32 v[78:79], v[138:139], v[158:159], v[78:79]
	v_mov_b32_e32 v135, v19
	v_cndmask_b32_e64 v156, v18, v156, s[6:7]
	v_cndmask_b32_e64 v158, v157, v214, s[4:5]
	v_mov_b32_e32 v18, v19
	v_mov_b32_e32 v157, v19
	v_mov_b32_dpp v135, v81 row_shr:2 row_mask:0xf bank_mask:0xf
	v_mov_b32_dpp v18, v83 row_shr:1 row_mask:0xf bank_mask:0xf
	v_mov_b32_dpp v157, v215 row_shl:1 row_mask:0xf bank_mask:0xf
	v_pk_fma_f32 v[80:81], v[80:81], v[144:145], v[148:149]
	v_cndmask_b32_e64 v157, v18, v157, s[6:7]
	v_pk_fma_f32 v[80:81], v[140:141], v[132:133], v[80:81]
	v_mov_b32_e32 v18, v19
	v_mov_b32_e32 v133, v19
	v_mov_b32_e32 v132, v19
	v_cndmask_b32_e64 v135, v135, v213, s[4:5]
	v_mov_b32_dpp v18, v96 row_shr:1 row_mask:0xf bank_mask:0xf
	v_mov_b32_dpp v133, v96 row_shr:2 row_mask:0xf bank_mask:0xf
	v_mov_b32_dpp v132, v216 row_shl:1 row_mask:0xf bank_mask:0xf
	v_pk_fma_f32 v[80:81], v[136:137], v[134:135], v[80:81]
	v_cndmask_b32_e64 v132, v18, v132, s[6:7]
	v_cndmask_b32_e64 v134, v133, v216, s[4:5]
	v_mov_b32_e32 v18, v19
	v_mov_b32_e32 v135, v19
	v_mov_b32_e32 v133, v19
	v_mov_b32_dpp v18, v97 row_shr:1 row_mask:0xf bank_mask:0xf
	v_mov_b32_dpp v135, v97 row_shr:2 row_mask:0xf bank_mask:0xf
	v_mov_b32_dpp v133, v217 row_shl:1 row_mask:0xf bank_mask:0xf
	v_cndmask_b32_e64 v133, v18, v133, s[6:7]
	v_cndmask_b32_e64 v135, v135, v217, s[4:5]
	v_mov_b32_e32 v18, v19
	v_mov_b32_e32 v153, v19
	v_mov_b32_e32 v152, v19
	v_mov_b32_e32 v159, v19
	v_mov_b32_dpp v18, v98 row_shr:1 row_mask:0xf bank_mask:0xf
;     __device__ __forceinline__ void sample(f32x4 (&acc)[2][2][4][2], const Unit& u, int row0t, int wr, int wc, int fr, int fq) const {
;     ...
;         const unsigned stoff = (unsigned)((sql * 2 + (t & 1)) * DFF2 + ca) * 4u;
; #pragma unroll
;         for (int n = 0; n < 2; ++n) {
;             const unsigned cso = (unsigned)((ca + 4 * n) * 4);
;             const f32x4 w0 = *(const f32x4*)((const char*)cw + cso), w1 = *(const f32x4*)((const char*)(cw + DFF2) + cso), w2 = *(const f32x4*)((const char*)(cw + 2 * DFF2) + cso), bsv = *(const f32x4*)((const char*)cb + cso);
; #pragma unroll
;             for (int ai = 0; ai < 2; ++ai) {
; #pragma unroll
;                 for (int mp = 0; mp < 4; mp += 4) {
;                     f32x4 pv[4];
; #pragma unroll
;                     for (int k = 0; k < 4; ++k) { pv[k] = (f32x4){0.f, 0.f, 0.f, 0.f}; if (t < 2) pv[k] = *(const f32x4*)((const char*)st + stoff + (unsigned)(((16 * ai + 2 * (mp + k)) * 2 * DFF2 + 4 * n) * 4)); }
; #pragma unroll
;                     for (int k = 0; k < 4; ++k) acc[ai][0][mp + k][n] = conv4s(acc[ai][0][mp + k][n], pv[k], t, w0, w1, w2, bsv);
;                     __builtin_amdgcn_sched_barrier(0);
;                 }
;             }
;         }
;         asm volatile("" ::: "memory");
;         f32x4 wk[4];
;         u32x2 pend[4];
; #pragma unroll
;         for (int step = 0; step < 4; ++step) {
;             const int n = (step == 1 || step == 2) ? 1 : 0, ai = step >> 1;
;             f32x4 w0, w1, w2, bsv;
;             if (step != 2) { const unsigned cso = (unsigned)((DFF + ca + 4 * n) * 4);
;                 w0 = *(const f32x4*)((const char*)cw + cso); w1 = *(const f32x4*)((const char*)(cw + DFF2) + cso); w2 = *(const f32x4*)((const char*)(cw + 2 * DFF2) + cso); bsv = *(const f32x4*)((const char*)cb + cso);
;                 wk[0] = w0; wk[1] = w1; wk[2] = w2; wk[3] = bsv; }
;             else { w0 = wk[0]; w1 = wk[1]; w2 = wk[2]; bsv = wk[3]; }
; #pragma unroll
;             for (int mp = 0; mp < 4; mp += 4) {
;             f32x4 pv[4];
; #pragma unroll
;             for (int k = 0; k < 4; ++k) { pv[k] = (f32x4){0.f, 0.f, 0.f, 0.f}; if (t < 2) pv[k] = *(const f32x4*)((const char*)st + stoff + (unsigned)(((16 * ai + 2 * (mp + k)) * 2 * DFF2 + DFF + 4 * n) * 4)); }
; #pragma unroll
;             for (int k = 0; k < 4; ++k) { const int m = mp + k;
	v_mov_b32_dpp v153, v98 row_shr:2 row_mask:0xf bank_mask:0xf
	v_mov_b32_dpp v152, v218 row_shl:1 row_mask:0xf bank_mask:0xf
	v_mov_b32_dpp v159, v83 row_shr:2 row_mask:0xf bank_mask:0xf
	v_pk_fma_f32 v[82:83], v[82:83], v[146:147], v[150:151]
	v_cndmask_b32_e64 v152, v18, v152, s[6:7]
	v_cndmask_b32_e64 v154, v153, v218, s[4:5]
	v_mov_b32_e32 v18, v19
	v_mov_b32_e32 v153, v19
	v_pk_fma_f32 v[82:83], v[142:143], v[156:157], v[82:83]
	v_mov_b32_dpp v18, v99 row_shr:1 row_mask:0xf bank_mask:0xf
	v_mov_b32_e32 v156, v19
	v_mov_b32_dpp v153, v219 row_shl:1 row_mask:0xf bank_mask:0xf
	v_cndmask_b32_e64 v153, v18, v153, s[6:7]
	v_mov_b32_dpp v156, v99 row_shr:2 row_mask:0xf bank_mask:0xf
	v_pk_fma_f32 v[98:99], v[98:99], v[146:147], v[150:151]
	v_pk_fma_f32 v[96:97], v[96:97], v[144:145], v[148:149]
	v_cndmask_b32_e64 v159, v159, v215, s[4:5]
	v_cndmask_b32_e64 v155, v156, v219, s[4:5]
	v_pk_fma_f32 v[98:99], v[142:143], v[152:153], v[98:99]
	v_pk_fma_f32 v[96:97], v[140:141], v[132:133], v[96:97]
	v_pk_fma_f32 v[82:83], v[138:139], v[158:159], v[82:83]
	v_pk_fma_f32 v[98:99], v[138:139], v[154:155], v[98:99]
	v_pk_fma_f32 v[96:97], v[136:137], v[134:135], v[96:97]
	s_nop 0
	v_add_u32_e32 v170, 0x2c00, v176
	global_load_dwordx4 v[136:139], v170, s[0:1]
	global_load_dwordx4 v[140:143], v170, s[8:9]
	global_load_dwordx4 v[132:135], v170, s[96:97]
	global_load_dwordx4 v[144:147], v170, s[66:67]
	v_mov_b32_e32 v152, 0
	v_mov_b32_e32 v156, 0
	v_mov_b32_e32 v157, 0
	v_mov_b32_e32 v158, 0
	v_mov_b32_e32 v159, 0
	v_mov_b32_e32 v153, 0
	v_mov_b32_e32 v154, 0
	v_mov_b32_e32 v155, 0
	v_mov_b32_e32 v148, 0
	v_mov_b32_e32 v166, 0
	v_mov_b32_e32 v167, 0
	v_mov_b32_e32 v168, 0
	v_mov_b32_e32 v169, 0
	v_mov_b32_e32 v149, 0
	v_mov_b32_e32 v150, 0
	v_mov_b32_e32 v151, 0
	v_mov_b32_e32 v18, v19
	v_mov_b32_e32 v161, v19
	v_mov_b32_e32 v160, v19
	v_mov_b32_dpp v18, v92 row_shr:1 row_mask:0xf bank_mask:0xf
	v_mov_b32_dpp v161, v92 row_shr:2 row_mask:0xf bank_mask:0xf
	s_waitcnt vmcnt(0)
	v_mov_b32_e32 v204, 0
	v_mov_b32_e32 v205, 0
	v_mov_b32_e32 v206, 0
	v_mov_b32_e32 v207, 0
	v_mov_b32_e32 v208, 0
	v_mov_b32_e32 v209, 0
	v_mov_b32_e32 v210, 0
	v_mov_b32_e32 v211, 0
	v_mov_b32_e32 v212, 0
	v_mov_b32_e32 v213, 0
	v_mov_b32_e32 v214, 0
	v_mov_b32_e32 v215, 0
	v_mov_b32_e32 v216, 0
	v_mov_b32_e32 v217, 0
	v_mov_b32_e32 v218, 0
	v_mov_b32_e32 v219, 0
	s_and_saveexec_b64 s[100:101], s[4:5]
	s_cbranch_execz .Lspp_5
	s_mov_b64 s[98:99], 0x2c10
	v_lshl_add_u64 v[194:195], v[172:173], 0, s[98:99]
	global_load_dwordx4 v[204:207], v[194:195], off
	s_mov_b64 s[98:99], 0x18c10
	v_lshl_add_u64 v[194:195], v[172:173], 0, s[98:99]
	global_load_dwordx4 v[208:211], v[194:195], off
	s_mov_b64 s[98:99], 0x2ec10
	v_lshl_add_u64 v[194:195], v[172:173], 0, s[98:99]
	global_load_dwordx4 v[212:215], v[194:195], off
	s_mov_b64 s[98:99], 0x44c10
	v_lshl_add_u64 v[194:195], v[172:173], 0, s[98:99]
	global_load_dwordx4 v[216:219], v[194:195], off
.Lspp_5:
	s_or_b64 exec, exec, s[100:101]
	s_nop 4
	v_mov_b32_dpp v160, v178 row_shl:1 row_mask:0xf bank_mask:0xf
	v_cndmask_b32_e64 v160, v18, v160, s[6:7]
	v_cndmask_b32_e64 v156, v161, v178, s[4:5]
	v_mov_b32_e32 v18, v19
	v_mov_b32_e32 v162, v19
	v_mov_b32_e32 v161, v19
	v_mov_b32_dpp v18, v93 row_shr:1 row_mask:0xf bank_mask:0xf
	v_mov_b32_dpp v162, v93 row_shr:2 row_mask:0xf bank_mask:0xf
	v_mov_b32_dpp v161, v179 row_shl:1 row_mask:0xf bank_mask:0xf
	v_cndmask_b32_e64 v161, v18, v161, s[6:7]
	v_cndmask_b32_e64 v157, v162, v179, s[4:5]
	v_mov_b32_e32 v18, v19
	v_mov_b32_e32 v163, v19
	v_mov_b32_e32 v162, v19
	v_mov_b32_dpp v18, v94 row_shr:1 row_mask:0xf bank_mask:0xf
	v_mov_b32_dpp v163, v94 row_shr:2 row_mask:0xf bank_mask:0xf
	v_mov_b32_dpp v162, v180 row_shl:1 row_mask:0xf bank_mask:0xf
	v_cndmask_b32_e64 v162, v18, v162, s[6:7]
	v_cndmask_b32_e64 v158, v163, v180, s[4:5]
	v_mov_b32_e32 v18, v19
	v_mov_b32_e32 v163, v19
	v_mov_b32_e32 v164, v19
	v_mov_b32_dpp v18, v95 row_shr:1 row_mask:0xf bank_mask:0xf
	v_mov_b32_dpp v163, v181 row_shl:1 row_mask:0xf bank_mask:0xf
	v_mov_b32_dpp v164, v95 row_shr:2 row_mask:0xf bank_mask:0xf
	v_cndmask_b32_e64 v163, v18, v163, s[6:7]
	v_pk_fma_f32 v[94:95], v[94:95], v[142:143], v[146:147]
	v_pk_fma_f32 v[92:93], v[92:93], v[140:141], v[144:145]
	v_cndmask_b32_e64 v159, v164, v181, s[4:5]
	v_pk_fma_f32 v[94:95], v[138:139], v[162:163], v[94:95]
	v_pk_fma_f32 v[92:93], v[136:137], v[160:161], v[92:93]
	v_pk_fma_f32 v[164:165], v[134:135], v[158:159], v[94:95]
	v_pk_fma_f32 v[162:163], v[132:133], v[156:157], v[92:93]
	s_nop 0
	v_mov_b32_e32 v18, v19
	v_mov_b32_e32 v93, v19
	v_mov_b32_e32 v92, v19
	v_mov_b32_dpp v18, v88 row_shr:1 row_mask:0xf bank_mask:0xf
	v_mov_b32_dpp v93, v88 row_shr:2 row_mask:0xf bank_mask:0xf
	v_mov_b32_dpp v92, v182 row_shl:1 row_mask:0xf bank_mask:0xf
	v_cndmask_b32_e64 v92, v18, v92, s[6:7]
	v_cndmask_b32_e64 v94, v93, v182, s[4:5]
	v_mov_b32_e32 v18, v19
	v_mov_b32_e32 v95, v19
	v_mov_b32_e32 v93, v19
	v_mov_b32_dpp v18, v89 row_shr:1 row_mask:0xf bank_mask:0xf
	v_mov_b32_dpp v95, v89 row_shr:2 row_mask:0xf bank_mask:0xf
	v_mov_b32_dpp v93, v183 row_shl:1 row_mask:0xf bank_mask:0xf
	v_cndmask_b32_e64 v93, v18, v93, s[6:7]
	v_cndmask_b32_e64 v95, v95, v183, s[4:5]
	v_mov_b32_e32 v18, v19
	v_mov_b32_e32 v153, v19
	v_mov_b32_e32 v152, v19
	v_mov_b32_dpp v18, v90 row_shr:1 row_mask:0xf bank_mask:0xf
	v_mov_b32_dpp v153, v90 row_shr:2 row_mask:0xf bank_mask:0xf
	v_mov_b32_dpp v152, v184 row_shl:1 row_mask:0xf bank_mask:0xf
	v_cndmask_b32_e64 v152, v18, v152, s[6:7]
	v_cndmask_b32_e64 v154, v153, v184, s[4:5]
	v_mov_b32_e32 v18, v19
	v_mov_b32_e32 v153, v19
	v_mov_b32_e32 v156, v19
;     __device__ __forceinline__ f32x4 conv4s(const f32x4 c4, const f32x4 pv, int t, const f32x4 w0, const f32x4 w1, const f32x4 w2, const f32x4 bsv) const {
;         f32x4 p1, p2;
; #pragma unroll
;         for (int e = 0; e < 4; ++e) { p1[e] = dpp_f<0x111>(0.f, c4[e]); p2[e] = dpp_f<0x112>(0.f, c4[e]); const float q1 = dpp_f<0x101>(0.f, pv[e]);
;             p1[e] = t == 0 ? q1 : p1[e]; p2[e] = t < 2 ? pv[e] : p2[e]; }
;         f32x4 uu = bsv + w2 * c4 + w1 * p1 + w0 * p2;
;         asm volatile("" : "+v"(uu));
;     __device__ __forceinline__ void sample(f32x4 (&acc)[2][2][4][2], const Unit& u, int row0t, int wr, int wc, int fr, int fq) const {
;     ...
;         for (int step = 0; step < 4; ++step) {
;             const int n = (step == 1 || step == 2) ? 1 : 0, ai = step >> 1;
;             f32x4 w0, w1, w2, bsv;
;             if (step != 2) { const unsigned cso = (unsigned)((DFF + ca + 4 * n) * 4);
;                 w0 = *(const f32x4*)((const char*)cw + cso); w1 = *(const f32x4*)((const char*)(cw + DFF2) + cso); w2 = *(const f32x4*)((const char*)(cw + 2 * DFF2) + cso); bsv = *(const f32x4*)((const char*)cb + cso);
;                 wk[0] = w0; wk[1] = w1; wk[2] = w2; wk[3] = bsv; }
;             else { w0 = wk[0]; w1 = wk[1]; w2 = wk[2]; bsv = wk[3]; }
; #pragma unroll
;             for (int mp = 0; mp < 4; mp += 4) {
;             f32x4 pv[4];
; #pragma unroll
;             for (int k = 0; k < 4; ++k) { pv[k] = (f32x4){0.f, 0.f, 0.f, 0.f}; if (t < 2) pv[k] = *(const f32x4*)((const char*)st + stoff + (unsigned)(((16 * ai + 2 * (mp + k)) * 2 * DFF2 + DFF + 4 * n) * 4)); }
; #pragma unroll
;             for (int k = 0; k < 4; ++k) { const int m = mp + k;
;                 const f32x4 uu = conv4s(acc[ai][1][m][n], pv[k], t, w0, w1, w2, bsv);
;                 const f32x4 ua = acc[ai][0][m][n];
;                 u32x2 w; w.x = cvt_pk_bf16(silu_f(ua[0]) * uu[0], silu_f(ua[1]) * uu[1]); w.y = cvt_pk_bf16(silu_f(ua[2]) * uu[2], silu_f(ua[3]) * uu[3]);
;                 if ((step & 1) == 0) pend[m] = w;
;                 else { u32x4 o; if (n == 1) { o.x = pend[m].x; o.y = pend[m].y; o.z = w.x; o.w = w.y; } else { o.x = w.x; o.y = w.y; o.z = pend[m].x; o.w = pend[m].y; }
;                     *(u32x4*)((char*)act + rowoff0 + (unsigned)((ai * HALF + m * 16) * DFF * 2) + (unsigned)(ca * 2)) = o; }
;                 __builtin_amdgcn_sched_barrier(0);
	v_mov_b32_dpp v18, v91 row_shr:1 row_mask:0xf bank_mask:0xf
	v_mov_b32_dpp v153, v185 row_shl:1 row_mask:0xf bank_mask:0xf
	v_mov_b32_dpp v156, v91 row_shr:2 row_mask:0xf bank_mask:0xf
	v_cndmask_b32_e64 v153, v18, v153, s[6:7]
	v_pk_fma_f32 v[90:91], v[90:91], v[142:143], v[146:147]
	v_pk_fma_f32 v[88:89], v[88:89], v[140:141], v[144:145]
	v_cndmask_b32_e64 v155, v156, v185, s[4:5]
	v_pk_fma_f32 v[90:91], v[138:139], v[152:153], v[90:91]
	v_pk_fma_f32 v[88:89], v[136:137], v[92:93], v[88:89]
	v_pk_fma_f32 v[160:161], v[134:135], v[154:155], v[90:91]
	v_pk_fma_f32 v[158:159], v[132:133], v[94:95], v[88:89]
	s_nop 0
	v_mov_b32_e32 v18, v19
	v_mov_b32_e32 v89, v19
	v_mov_b32_e32 v88, v19
	v_mov_b32_dpp v18, v84 row_shr:1 row_mask:0xf bank_mask:0xf
	v_mov_b32_dpp v89, v84 row_shr:2 row_mask:0xf bank_mask:0xf
	v_mov_b32_dpp v88, v186 row_shl:1 row_mask:0xf bank_mask:0xf
	v_cndmask_b32_e64 v88, v18, v88, s[6:7]
	v_cndmask_b32_e64 v90, v89, v186, s[4:5]
	v_mov_b32_e32 v18, v19
	v_mov_b32_e32 v89, v19
	v_mov_b32_e32 v93, v19
	v_mov_b32_dpp v18, v85 row_shr:1 row_mask:0xf bank_mask:0xf
	v_mov_b32_dpp v89, v187 row_shl:1 row_mask:0xf bank_mask:0xf
	v_cndmask_b32_e64 v89, v18, v89, s[6:7]
	v_mov_b32_e32 v18, v19
	v_mov_b32_e32 v92, v19
	v_mov_b32_dpp v93, v86 row_shr:2 row_mask:0xf bank_mask:0xf
	v_mov_b32_dpp v18, v86 row_shr:1 row_mask:0xf bank_mask:0xf
	v_mov_b32_dpp v92, v188 row_shl:1 row_mask:0xf bank_mask:0xf
	v_cndmask_b32_e64 v92, v18, v92, s[6:7]
	v_cndmask_b32_e64 v94, v93, v188, s[4:5]
	v_mov_b32_e32 v18, v19
	v_mov_b32_e32 v93, v19
	v_mov_b32_e32 v91, v19
	v_mov_b32_dpp v18, v87 row_shr:1 row_mask:0xf bank_mask:0xf
	v_mov_b32_e32 v95, v19
	v_mov_b32_dpp v93, v189 row_shl:1 row_mask:0xf bank_mask:0xf
	v_mov_b32_dpp v91, v85 row_shr:2 row_mask:0xf bank_mask:0xf
	v_mov_b32_dpp v95, v87 row_shr:2 row_mask:0xf bank_mask:0xf
	v_cndmask_b32_e64 v93, v18, v93, s[6:7]
	v_pk_fma_f32 v[86:87], v[86:87], v[142:143], v[146:147]
	v_pk_fma_f32 v[84:85], v[84:85], v[140:141], v[144:145]
	v_cndmask_b32_e64 v91, v91, v187, s[4:5]
	v_cndmask_b32_e64 v95, v95, v189, s[4:5]
	v_pk_fma_f32 v[86:87], v[138:139], v[92:93], v[86:87]
	v_pk_fma_f32 v[84:85], v[136:137], v[88:89], v[84:85]
	v_pk_fma_f32 v[156:157], v[134:135], v[94:95], v[86:87]
	v_pk_fma_f32 v[154:155], v[132:133], v[90:91], v[84:85]
	s_nop 0
	v_mov_b32_e32 v18, v19
	v_mov_b32_e32 v85, v19
	v_mov_b32_e32 v84, v19
	v_mov_b32_dpp v18, v68 row_shr:1 row_mask:0xf bank_mask:0xf
	v_mov_b32_dpp v85, v68 row_shr:2 row_mask:0xf bank_mask:0xf
	v_mov_b32_dpp v84, v190 row_shl:1 row_mask:0xf bank_mask:0xf
	v_cndmask_b32_e64 v84, v18, v84, s[6:7]
	v_cndmask_b32_e64 v86, v85, v190, s[4:5]
	v_mov_b32_e32 v18, v19
	v_mov_b32_e32 v85, v19
	v_mov_b32_e32 v89, v19
	v_mov_b32_dpp v18, v69 row_shr:1 row_mask:0xf bank_mask:0xf
	v_mov_b32_dpp v85, v191 row_shl:1 row_mask:0xf bank_mask:0xf
	v_cndmask_b32_e64 v85, v18, v85, s[6:7]
	v_mov_b32_e32 v18, v19
	v_mov_b32_e32 v88, v19
	v_mov_b32_dpp v89, v70 row_shr:2 row_mask:0xf bank_mask:0xf
	v_mov_b32_dpp v18, v70 row_shr:1 row_mask:0xf bank_mask:0xf
	v_mov_b32_dpp v88, v192 row_shl:1 row_mask:0xf bank_mask:0xf
	v_cndmask_b32_e64 v88, v18, v88, s[6:7]
	v_cndmask_b32_e64 v90, v89, v192, s[4:5]
	v_mov_b32_e32 v18, v19
	v_mov_b32_e32 v89, v19
	v_mov_b32_e32 v87, v19
	v_mov_b32_dpp v18, v71 row_shr:1 row_mask:0xf bank_mask:0xf
	v_mov_b32_e32 v91, v19
	v_mov_b32_dpp v89, v193 row_shl:1 row_mask:0xf bank_mask:0xf
	v_mov_b32_dpp v87, v69 row_shr:2 row_mask:0xf bank_mask:0xf
	v_mov_b32_dpp v91, v71 row_shr:2 row_mask:0xf bank_mask:0xf
	v_cndmask_b32_e64 v89, v18, v89, s[6:7]
	v_pk_fma_f32 v[70:71], v[70:71], v[142:143], v[146:147]
	v_pk_fma_f32 v[68:69], v[68:69], v[140:141], v[144:145]
	v_cndmask_b32_e64 v87, v87, v191, s[4:5]
	v_cndmask_b32_e64 v91, v91, v193, s[4:5]
	v_pk_fma_f32 v[70:71], v[138:139], v[88:89], v[70:71]
	v_pk_fma_f32 v[68:69], v[136:137], v[84:85], v[68:69]
	v_pk_fma_f32 v[152:153], v[134:135], v[90:91], v[70:71]
	v_pk_fma_f32 v[150:151], v[132:133], v[86:87], v[68:69]
	s_nop 0
	v_add_u32_e32 v18, 0x2c10, v176
	global_load_dwordx4 v[84:87], v18, s[0:1]
	global_load_dwordx4 v[88:91], v18, s[8:9]
	global_load_dwordx4 v[68:71], v18, s[96:97]
	global_load_dwordx4 v[92:95], v18, s[66:67]
	v_mov_b32_e32 v140, 0
	v_mov_b32_e32 v144, 0
	v_mov_b32_e32 v145, 0
	v_mov_b32_e32 v146, 0
	v_mov_b32_e32 v147, 0
	v_mov_b32_e32 v141, 0
	v_mov_b32_e32 v142, 0
	v_mov_b32_e32 v143, 0
	v_mov_b32_e32 v132, 0
	v_mov_b32_e32 v136, 0
	v_mov_b32_e32 v137, 0
	v_mov_b32_e32 v138, 0
	v_mov_b32_e32 v139, 0
	v_mov_b32_e32 v133, 0
	v_mov_b32_e32 v134, 0
	v_mov_b32_e32 v135, 0
	v_mul_f32_e32 v18, 0xbfb8aa3b, v114
	v_exp_f32_e32 v18, v18
	s_movk_i32 s2, 0x1600
	v_add_f32_e32 v18, 1.0, v18
	v_rcp_f32_e32 v148, v18
	v_mul_f32_e32 v18, 0xbfb8aa3b, v115
	v_exp_f32_e32 v18, v18
	s_nop 0
	v_add_f32_e32 v18, 1.0, v18
	v_rcp_f32_e32 v149, v18
	v_mul_f32_e32 v18, 0xbfb8aa3b, v112
	v_exp_f32_e32 v18, v18
	v_pk_mul_f32 v[114:115], v[114:115], v[148:149]
	s_nop 0
	v_pk_mul_f32 v[114:115], v[114:115], v[164:165]
	v_add_f32_e32 v18, 1.0, v18
	v_cvt_pk_bf16_f32 v149, v114, v115
	v_rcp_f32_e32 v114, v18
	v_mul_f32_e32 v18, 0xbfb8aa3b, v113
	v_exp_f32_e32 v18, v18
	s_nop 0
	v_add_f32_e32 v18, 1.0, v18
	v_rcp_f32_e32 v115, v18
	v_mul_f32_e32 v18, 0xbfb8aa3b, v110
	v_exp_f32_e32 v18, v18
	v_pk_mul_f32 v[112:113], v[112:113], v[114:115]
	s_nop 0
	v_pk_mul_f32 v[112:113], v[112:113], v[162:163]
	v_add_f32_e32 v18, 1.0, v18
	v_cvt_pk_bf16_f32 v148, v112, v113
	v_rcp_f32_e32 v112, v18
	v_mul_f32_e32 v18, 0xbfb8aa3b, v111
	v_exp_f32_e32 v18, v18
	v_mov_b32_e32 v114, v19
	v_mov_b32_e32 v115, v19
	v_add_f32_e32 v18, 1.0, v18
	v_rcp_f32_e32 v113, v18
	v_mul_f32_e32 v18, 0xbfb8aa3b, v108
	v_exp_f32_e32 v18, v18
	s_waitcnt vmcnt(0)
	v_mov_b32_e32 v178, 0
	v_mov_b32_e32 v179, 0
	v_mov_b32_e32 v180, 0
	v_mov_b32_e32 v181, 0
	v_mov_b32_e32 v182, 0
	v_mov_b32_e32 v183, 0
	v_mov_b32_e32 v184, 0
	v_mov_b32_e32 v185, 0
	v_mov_b32_e32 v186, 0
	v_mov_b32_e32 v187, 0
	v_mov_b32_e32 v188, 0
	v_mov_b32_e32 v189, 0
	v_mov_b32_e32 v190, 0
	v_mov_b32_e32 v191, 0
	v_mov_b32_e32 v192, 0
	v_mov_b32_e32 v193, 0
	s_and_saveexec_b64 s[100:101], s[4:5]
	s_cbranch_execz .Lspp_6
	s_mov_b64 s[98:99], 0xb2c10
	v_lshl_add_u64 v[194:195], v[172:173], 0, s[98:99]
	global_load_dwordx4 v[178:181], v[194:195], off
	s_mov_b64 s[98:99], 0xc8c10
	v_lshl_add_u64 v[194:195], v[172:173], 0, s[98:99]
	global_load_dwordx4 v[182:185], v[194:195], off
	s_mov_b64 s[98:99], 0xdec10
	v_lshl_add_u64 v[194:195], v[172:173], 0, s[98:99]
	global_load_dwordx4 v[186:189], v[194:195], off
	s_mov_b64 s[98:99], 0xf4c10
	v_lshl_add_u64 v[194:195], v[172:173], 0, s[98:99]
	global_load_dwordx4 v[190:193], v[194:195], off
;     __device__ __forceinline__ f32x4 conv4s(const f32x4 c4, const f32x4 pv, int t, const f32x4 w0, const f32x4 w1, const f32x4 w2, const f32x4 bsv) const {
;         f32x4 p1, p2;
; #pragma unroll
;         for (int e = 0; e < 4; ++e) { p1[e] = dpp_f<0x111>(0.f, c4[e]); p2[e] = dpp_f<0x112>(0.f, c4[e]); const float q1 = dpp_f<0x101>(0.f, pv[e]);
;             p1[e] = t == 0 ? q1 : p1[e]; p2[e] = t < 2 ? pv[e] : p2[e]; }
;         f32x4 uu = bsv + w2 * c4 + w1 * p1 + w0 * p2;
;         asm volatile("" : "+v"(uu));
;     __device__ __forceinline__ void sample(f32x4 (&acc)[2][2][4][2], const Unit& u, int row0t, int wr, int wc, int fr, int fq) const {
;     ...
;         for (int step = 0; step < 4; ++step) {
;             const int n = (step == 1 || step == 2) ? 1 : 0, ai = step >> 1;
;             f32x4 w0, w1, w2, bsv;
;             if (step != 2) { const unsigned cso = (unsigned)((DFF + ca + 4 * n) * 4);
;                 w0 = *(const f32x4*)((const char*)cw + cso); w1 = *(const f32x4*)((const char*)(cw + DFF2) + cso); w2 = *(const f32x4*)((const char*)(cw + 2 * DFF2) + cso); bsv = *(const f32x4*)((const char*)cb + cso);
;                 wk[0] = w0; wk[1] = w1; wk[2] = w2; wk[3] = bsv; }
;             else { w0 = wk[0]; w1 = wk[1]; w2 = wk[2]; bsv = wk[3]; }
; #pragma unroll
;             for (int mp = 0; mp < 4; mp += 4) {
;             f32x4 pv[4];
; #pragma unroll
;             for (int k = 0; k < 4; ++k) { pv[k] = (f32x4){0.f, 0.f, 0.f, 0.f}; if (t < 2) pv[k] = *(const f32x4*)((const char*)st + stoff + (unsigned)(((16 * ai + 2 * (mp + k)) * 2 * DFF2 + DFF + 4 * n) * 4)); }
; #pragma unroll
;             for (int k = 0; k < 4; ++k) { const int m = mp + k;
;                 const f32x4 uu = conv4s(acc[ai][1][m][n], pv[k], t, w0, w1, w2, bsv);
;                 const f32x4 ua = acc[ai][0][m][n];
;                 u32x2 w; w.x = cvt_pk_bf16(silu_f(ua[0]) * uu[0], silu_f(ua[1]) * uu[1]); w.y = cvt_pk_bf16(silu_f(ua[2]) * uu[2], silu_f(ua[3]) * uu[3]);
;                 if ((step & 1) == 0) pend[m] = w;
;                 else { u32x4 o; if (n == 1) { o.x = pend[m].x; o.y = pend[m].y; o.z = w.x; o.w = w.y; } else { o.x = w.x; o.y = w.y; o.z = pend[m].x; o.w = pend[m].y; }
;                     *(u32x4*)((char*)act + rowoff0 + (unsigned)((ai * HALF + m * 16) * DFF * 2) + (unsigned)(ca * 2)) = o; }
;                 __builtin_amdgcn_sched_barrier(0);
.Lspp_6:
	s_or_b64 exec, exec, s[100:101]
	s_nop 4
	v_mov_b32_dpp v114, v206 row_shl:1 row_mask:0xf bank_mask:0xf
	v_pk_mul_f32 v[110:111], v[110:111], v[112:113]
	v_mov_b32_dpp v115, v67 row_shr:2 row_mask:0xf bank_mask:0xf
	v_add_f32_e32 v18, 1.0, v18
	v_rcp_f32_e32 v112, v18
	v_mul_f32_e32 v18, 0xbfb8aa3b, v109
	v_exp_f32_e32 v18, v18
	v_pk_mul_f32 v[110:111], v[110:111], v[160:161]
	v_cndmask_b32_e64 v115, v115, v207, s[4:5]
	v_cvt_pk_bf16_f32 v111, v110, v111
	v_add_f32_e32 v18, 1.0, v18
	v_rcp_f32_e32 v113, v18
	v_mul_f32_e32 v18, 0xbfb8aa3b, v106
	v_exp_f32_e32 v18, v18
	v_pk_mul_f32 v[108:109], v[108:109], v[112:113]
	s_nop 0
	v_pk_mul_f32 v[108:109], v[108:109], v[158:159]
	v_add_f32_e32 v18, 1.0, v18
	v_cvt_pk_bf16_f32 v110, v108, v109
	v_rcp_f32_e32 v108, v18
	v_mul_f32_e32 v18, 0xbfb8aa3b, v107
	v_exp_f32_e32 v18, v18
	v_mov_b32_e32 v112, v19
	v_mov_b32_e32 v113, v19
	v_add_f32_e32 v18, 1.0, v18
	v_rcp_f32_e32 v109, v18
	v_mul_f32_e32 v18, 0xbfb8aa3b, v104
	v_exp_f32_e32 v18, v18
	v_mov_b32_dpp v112, v205 row_shl:1 row_mask:0xf bank_mask:0xf
	v_pk_mul_f32 v[106:107], v[106:107], v[108:109]
	v_mov_b32_dpp v113, v66 row_shr:2 row_mask:0xf bank_mask:0xf
	v_add_f32_e32 v18, 1.0, v18
	v_rcp_f32_e32 v108, v18
	v_mul_f32_e32 v18, 0xbfb8aa3b, v105
	v_exp_f32_e32 v18, v18
	v_pk_mul_f32 v[106:107], v[106:107], v[156:157]
	v_add_f32_e32 v18, 1.0, v18
	v_rcp_f32_e32 v109, v18
	v_mul_f32_e32 v18, 0xbfb8aa3b, v102
	v_exp_f32_e32 v18, v18
	v_cvt_pk_bf16_f32 v107, v106, v107
	v_pk_mul_f32 v[104:105], v[104:105], v[108:109]
	v_mov_b32_e32 v108, v19
	v_pk_mul_f32 v[104:105], v[104:105], v[154:155]
	v_add_f32_e32 v18, 1.0, v18
	v_cvt_pk_bf16_f32 v106, v104, v105
	v_rcp_f32_e32 v104, v18
	v_mul_f32_e32 v18, 0xbfb8aa3b, v103
	v_exp_f32_e32 v18, v18
	v_mov_b32_dpp v108, v204 row_shl:1 row_mask:0xf bank_mask:0xf
	v_mov_b32_e32 v109, v19
	v_add_f32_e32 v18, 1.0, v18
	v_rcp_f32_e32 v105, v18
	v_mul_f32_e32 v18, 0xbfb8aa3b, v100
	v_exp_f32_e32 v18, v18
	v_mov_b32_dpp v109, v65 row_shr:2 row_mask:0xf bank_mask:0xf
	v_pk_mul_f32 v[102:103], v[102:103], v[104:105]
	v_cndmask_b32_e64 v109, v109, v205, s[4:5]
	v_add_f32_e32 v18, 1.0, v18
	v_rcp_f32_e32 v104, v18
	v_mul_f32_e32 v18, 0xbfb8aa3b, v101
	v_exp_f32_e32 v18, v18
	v_pk_mul_f32 v[102:103], v[102:103], v[152:153]
	v_add_f32_e32 v18, 1.0, v18
	v_rcp_f32_e32 v105, v18
	v_mul_lo_u32 v18, v174, s2
	v_cvt_pk_bf16_f32 v103, v102, v103
	v_pk_mul_f32 v[100:101], v[100:101], v[104:105]
	v_mov_b32_e32 v104, v19
	v_mov_b32_e32 v105, v19
	v_pk_mul_f32 v[100:101], v[100:101], v[150:151]
	v_mov_b32_dpp v104, v64 row_shr:1 row_mask:0xf bank_mask:0xf
	v_mov_b32_dpp v105, v64 row_shr:2 row_mask:0xf bank_mask:0xf
	v_cndmask_b32_e64 v104, v104, v108, s[6:7]
	v_cndmask_b32_e64 v108, v105, v204, s[4:5]
	v_mov_b32_e32 v105, v19
	v_mov_b32_e32 v144, v19
	v_cvt_pk_bf16_f32 v102, v100, v101
	v_mov_b32_dpp v105, v65 row_shr:1 row_mask:0xf bank_mask:0xf
	v_cndmask_b32_e64 v105, v105, v112, s[6:7]
	v_pk_fma_f32 v[64:65], v[64:65], v[88:89], v[92:93]
	v_mov_b32_e32 v112, v19
	v_pk_fma_f32 v[64:65], v[84:85], v[104:105], v[64:65]
	v_mul_f32_e32 v104, 0xbfb8aa3b, v128
	v_mul_f32_e32 v105, 0xbfb8aa3b, v129
	v_exp_f32_e32 v104, v104
	v_exp_f32_e32 v105, v105
	v_mov_b32_dpp v112, v66 row_shr:1 row_mask:0xf bank_mask:0xf
	v_cndmask_b32_e64 v112, v112, v114, s[6:7]
	v_cndmask_b32_e64 v114, v113, v206, s[4:5]
	v_mov_b32_e32 v113, v19
	v_add_f32_e32 v104, 1.0, v104
	v_add_f32_e32 v105, 1.0, v105
	v_mov_b32_dpp v113, v67 row_shr:1 row_mask:0xf bank_mask:0xf
	v_mov_b32_dpp v144, v207 row_shl:1 row_mask:0xf bank_mask:0xf
	v_rcp_f32_e32 v104, v104
	v_rcp_f32_e32 v105, v105
	v_cndmask_b32_e64 v113, v113, v144, s[6:7]
	v_pk_fma_f32 v[66:67], v[66:67], v[90:91], v[94:95]
	v_pk_fma_f32 v[64:65], v[68:69], v[108:109], v[64:65]
	v_pk_fma_f32 v[66:67], v[86:87], v[112:113], v[66:67]
	v_pk_mul_f32 v[104:105], v[128:129], v[104:105]
	v_pk_fma_f32 v[66:67], v[70:71], v[114:115], v[66:67]
	v_lshlrev_b32_e32 v100, 1, v175
	v_mov_b32_e32 v101, v19
	v_pk_mul_f32 v[64:65], v[104:105], v[64:65]
	s_nop 0
	v_cvt_pk_bf16_f32 v150, v64, v65
	v_mul_f32_e32 v64, 0xbfb8aa3b, v130
	v_mul_f32_e32 v65, 0xbfb8aa3b, v131
	v_exp_f32_e32 v64, v64
	v_exp_f32_e32 v65, v65
	v_add_f32_e32 v64, 1.0, v64
	v_add_f32_e32 v65, 1.0, v65
	v_rcp_f32_e32 v64, v64
	v_rcp_f32_e32 v65, v65
	s_nop 0
	v_pk_mul_f32 v[64:65], v[130:131], v[64:65]
	s_nop 0
	v_pk_mul_f32 v[64:65], v[64:65], v[66:67]
	s_nop 0
	v_cvt_pk_bf16_f32 v151, v64, v65
	v_lshl_add_u64 v[64:65], s[70:71], 0, v[18:19]
	v_lshl_add_u64 v[114:115], v[64:65], 0, v[100:101]
	global_store_dwordx4 v[114:115], v[148:151], off
	v_mov_b32_e32 v18, v19
	v_mov_b32_e32 v65, v19
	v_mov_b32_e32 v64, v19
	v_mov_b32_dpp v18, v60 row_shr:1 row_mask:0xf bank_mask:0xf
	v_mov_b32_dpp v65, v60 row_shr:2 row_mask:0xf bank_mask:0xf
	v_mov_b32_dpp v64, v208 row_shl:1 row_mask:0xf bank_mask:0xf
	v_cndmask_b32_e64 v64, v18, v64, s[6:7]
	v_cndmask_b32_e64 v66, v65, v208, s[4:5]
	v_mov_b32_e32 v18, v19
	v_mov_b32_e32 v65, v19
	v_mov_b32_e32 v100, v19
	v_mov_b32_dpp v18, v61 row_shr:1 row_mask:0xf bank_mask:0xf
	v_mov_b32_dpp v65, v209 row_shl:1 row_mask:0xf bank_mask:0xf
	v_cndmask_b32_e64 v65, v18, v65, s[6:7]
	v_mov_b32_e32 v18, v19
	v_mov_b32_dpp v101, v62 row_shr:2 row_mask:0xf bank_mask:0xf
	v_mov_b32_dpp v100, v210 row_shl:1 row_mask:0xf bank_mask:0xf
	v_mov_b32_dpp v18, v62 row_shr:1 row_mask:0xf bank_mask:0xf
	v_cndmask_b32_e64 v100, v18, v100, s[6:7]
	v_cndmask_b32_e64 v104, v101, v210, s[4:5]
	v_mov_b32_e32 v18, v19
	v_mov_b32_e32 v101, v19
	v_mov_b32_e32 v67, v19
	v_mov_b32_dpp v18, v63 row_shr:1 row_mask:0xf bank_mask:0xf
;     __device__ __forceinline__ f32x4 conv4s(const f32x4 c4, const f32x4 pv, int t, const f32x4 w0, const f32x4 w1, const f32x4 w2, const f32x4 bsv) const {
;         f32x4 p1, p2;
; #pragma unroll
;         for (int e = 0; e < 4; ++e) { p1[e] = dpp_f<0x111>(0.f, c4[e]); p2[e] = dpp_f<0x112>(0.f, c4[e]); const float q1 = dpp_f<0x101>(0.f, pv[e]);
;             p1[e] = t == 0 ? q1 : p1[e]; p2[e] = t < 2 ? pv[e] : p2[e]; }
;         f32x4 uu = bsv + w2 * c4 + w1 * p1 + w0 * p2;
;         asm volatile("" : "+v"(uu));
;     __device__ __forceinline__ void sample(f32x4 (&acc)[2][2][4][2], const Unit& u, int row0t, int wr, int wc, int fr, int fq) const {
;     ...
;         for (int step = 0; step < 4; ++step) {
;             const int n = (step == 1 || step == 2) ? 1 : 0, ai = step >> 1;
;             f32x4 w0, w1, w2, bsv;
;             if (step != 2) { const unsigned cso = (unsigned)((DFF + ca + 4 * n) * 4);
;                 w0 = *(const f32x4*)((const char*)cw + cso); w1 = *(const f32x4*)((const char*)(cw + DFF2) + cso); w2 = *(const f32x4*)((const char*)(cw + 2 * DFF2) + cso); bsv = *(const f32x4*)((const char*)cb + cso);
;                 wk[0] = w0; wk[1] = w1; wk[2] = w2; wk[3] = bsv; }
;             else { w0 = wk[0]; w1 = wk[1]; w2 = wk[2]; bsv = wk[3]; }
; #pragma unroll
;             for (int mp = 0; mp < 4; mp += 4) {
;             f32x4 pv[4];
; #pragma unroll
;             for (int k = 0; k < 4; ++k) { pv[k] = (f32x4){0.f, 0.f, 0.f, 0.f}; if (t < 2) pv[k] = *(const f32x4*)((const char*)st + stoff + (unsigned)(((16 * ai + 2 * (mp + k)) * 2 * DFF2 + DFF + 4 * n) * 4)); }
; #pragma unroll
;             for (int k = 0; k < 4; ++k) { const int m = mp + k;
;                 const f32x4 uu = conv4s(acc[ai][1][m][n], pv[k], t, w0, w1, w2, bsv);
;                 const f32x4 ua = acc[ai][0][m][n];
;                 u32x2 w; w.x = cvt_pk_bf16(silu_f(ua[0]) * uu[0], silu_f(ua[1]) * uu[1]); w.y = cvt_pk_bf16(silu_f(ua[2]) * uu[2], silu_f(ua[3]) * uu[3]);
;                 if ((step & 1) == 0) pend[m] = w;
;                 else { u32x4 o; if (n == 1) { o.x = pend[m].x; o.y = pend[m].y; o.z = w.x; o.w = w.y; } else { o.x = w.x; o.y = w.y; o.z = pend[m].x; o.w = pend[m].y; }
;                     *(u32x4*)((char*)act + rowoff0 + (unsigned)((ai * HALF + m * 16) * DFF * 2) + (unsigned)(ca * 2)) = o; }
;                 __builtin_amdgcn_sched_barrier(0);
	v_mov_b32_dpp v101, v211 row_shl:1 row_mask:0xf bank_mask:0xf
	v_mov_b32_dpp v67, v61 row_shr:2 row_mask:0xf bank_mask:0xf
	v_cndmask_b32_e64 v101, v18, v101, s[6:7]
	v_pk_fma_f32 v[60:61], v[60:61], v[88:89], v[92:93]
	v_mul_f32_e32 v18, 0xbfb8aa3b, v124
	v_pk_fma_f32 v[60:61], v[84:85], v[64:65], v[60:61]
	v_exp_f32_e32 v18, v18
	v_mul_f32_e32 v64, 0xbfb8aa3b, v125
	v_exp_f32_e32 v65, v64
	v_cndmask_b32_e64 v67, v67, v209, s[4:5]
	v_add_f32_e32 v18, 1.0, v18
	v_rcp_f32_e32 v64, v18
	v_add_f32_e32 v18, 1.0, v65
	v_mul_f32_e32 v65, 0xbfb8aa3b, v126
	v_pk_fma_f32 v[60:61], v[68:69], v[66:67], v[60:61]
	v_exp_f32_e32 v66, v65
	v_mul_f32_e32 v65, 0xbfb8aa3b, v127
	v_exp_f32_e32 v67, v65
	v_mov_b32_e32 v105, v19
	v_rcp_f32_e32 v65, v18
	v_add_f32_e32 v18, 1.0, v66
	v_mov_b32_dpp v105, v63 row_shr:2 row_mask:0xf bank_mask:0xf
	v_pk_fma_f32 v[62:63], v[62:63], v[90:91], v[94:95]
	v_rcp_f32_e32 v66, v18
	v_add_f32_e32 v18, 1.0, v67
	v_cndmask_b32_e64 v105, v105, v211, s[4:5]
	v_pk_fma_f32 v[62:63], v[86:87], v[100:101], v[62:63]
	v_rcp_f32_e32 v67, v18
	v_pk_fma_f32 v[62:63], v[70:71], v[104:105], v[62:63]
	v_pk_mul_f32 v[64:65], v[124:125], v[64:65]
	s_mov_b32 s2, 0x16000
	v_pk_mul_f32 v[60:61], v[64:65], v[60:61]
	s_nop 0
	v_cvt_pk_bf16_f32 v112, v60, v61
	v_pk_mul_f32 v[60:61], v[126:127], v[66:67]
	s_nop 0
	v_pk_mul_f32 v[60:61], v[60:61], v[62:63]
	s_nop 0
	v_cvt_pk_bf16_f32 v113, v60, v61
	v_add_co_u32_e32 v60, vcc, s2, v114
	s_nop 1
	v_addc_co_u32_e32 v61, vcc, 0, v115, vcc
	global_store_dwordx4 v[60:61], v[110:113], off
	v_mov_b32_e32 v18, v19
	v_mov_b32_e32 v61, v19
	v_mov_b32_e32 v60, v19
	v_mov_b32_dpp v18, v56 row_shr:1 row_mask:0xf bank_mask:0xf
	v_mov_b32_dpp v61, v56 row_shr:2 row_mask:0xf bank_mask:0xf
	v_mov_b32_dpp v60, v212 row_shl:1 row_mask:0xf bank_mask:0xf
	v_cndmask_b32_e64 v60, v18, v60, s[6:7]
	v_cndmask_b32_e64 v62, v61, v212, s[4:5]
	v_mov_b32_e32 v18, v19
	v_mov_b32_e32 v61, v19
	v_mov_b32_e32 v65, v19
	v_mov_b32_dpp v18, v57 row_shr:1 row_mask:0xf bank_mask:0xf
	v_mov_b32_dpp v61, v213 row_shl:1 row_mask:0xf bank_mask:0xf
	v_cndmask_b32_e64 v61, v18, v61, s[6:7]
	v_mov_b32_e32 v18, v19
	v_mov_b32_e32 v64, v19
	v_mov_b32_dpp v65, v58 row_shr:2 row_mask:0xf bank_mask:0xf
	v_mov_b32_dpp v18, v58 row_shr:1 row_mask:0xf bank_mask:0xf
	v_mov_b32_dpp v64, v214 row_shl:1 row_mask:0xf bank_mask:0xf
	v_cndmask_b32_e64 v64, v18, v64, s[6:7]
	v_cndmask_b32_e64 v66, v65, v214, s[4:5]
	v_mov_b32_e32 v18, v19
	v_mov_b32_e32 v65, v19
	v_mov_b32_e32 v63, v19
	v_mov_b32_dpp v18, v59 row_shr:1 row_mask:0xf bank_mask:0xf
	v_mov_b32_dpp v65, v215 row_shl:1 row_mask:0xf bank_mask:0xf
	v_mov_b32_dpp v63, v57 row_shr:2 row_mask:0xf bank_mask:0xf
	v_cndmask_b32_e64 v65, v18, v65, s[6:7]
	v_pk_fma_f32 v[56:57], v[56:57], v[88:89], v[92:93]
	v_mul_f32_e32 v18, 0xbfb8aa3b, v120
	v_pk_fma_f32 v[56:57], v[84:85], v[60:61], v[56:57]
	v_exp_f32_e32 v18, v18
	v_mul_f32_e32 v60, 0xbfb8aa3b, v121
	v_exp_f32_e32 v61, v60
	v_cndmask_b32_e64 v63, v63, v213, s[4:5]
	v_add_f32_e32 v18, 1.0, v18
	v_rcp_f32_e32 v60, v18
	v_add_f32_e32 v18, 1.0, v61
	v_mul_f32_e32 v61, 0xbfb8aa3b, v122
	v_pk_fma_f32 v[56:57], v[68:69], v[62:63], v[56:57]
	v_exp_f32_e32 v62, v61
	v_mul_f32_e32 v61, 0xbfb8aa3b, v123
	v_exp_f32_e32 v63, v61
	v_mov_b32_e32 v67, v19
	v_rcp_f32_e32 v61, v18
	v_add_f32_e32 v18, 1.0, v62
	v_mov_b32_dpp v67, v59 row_shr:2 row_mask:0xf bank_mask:0xf
	v_pk_fma_f32 v[58:59], v[58:59], v[90:91], v[94:95]
	v_rcp_f32_e32 v62, v18
	v_add_f32_e32 v18, 1.0, v63
	v_cndmask_b32_e64 v67, v67, v215, s[4:5]
	v_pk_fma_f32 v[58:59], v[86:87], v[64:65], v[58:59]
	v_rcp_f32_e32 v63, v18
	v_pk_fma_f32 v[58:59], v[70:71], v[66:67], v[58:59]
	v_pk_mul_f32 v[60:61], v[120:121], v[60:61]
	s_mov_b32 s2, 0x2c000
	v_pk_mul_f32 v[56:57], v[60:61], v[56:57]
	s_nop 0
	v_cvt_pk_bf16_f32 v108, v56, v57
	v_pk_mul_f32 v[56:57], v[122:123], v[62:63]
	s_nop 0
	v_pk_mul_f32 v[56:57], v[56:57], v[58:59]
	s_nop 0
	v_cvt_pk_bf16_f32 v109, v56, v57
	v_add_co_u32_e32 v56, vcc, s2, v114
	s_nop 1
	v_addc_co_u32_e32 v57, vcc, 0, v115, vcc
	global_store_dwordx4 v[56:57], v[106:109], off
	v_mov_b32_e32 v18, v19
	v_mov_b32_e32 v57, v19
	v_mov_b32_e32 v56, v19
	v_mov_b32_dpp v18, v32 row_shr:1 row_mask:0xf bank_mask:0xf
	v_mov_b32_dpp v57, v32 row_shr:2 row_mask:0xf bank_mask:0xf
	v_mov_b32_dpp v56, v216 row_shl:1 row_mask:0xf bank_mask:0xf
	v_cndmask_b32_e64 v56, v18, v56, s[6:7]
	v_cndmask_b32_e64 v58, v57, v216, s[4:5]
	v_mov_b32_e32 v18, v19
	v_mov_b32_e32 v57, v19
	v_mov_b32_e32 v61, v19
	v_mov_b32_dpp v18, v33 row_shr:1 row_mask:0xf bank_mask:0xf
	v_mov_b32_dpp v57, v217 row_shl:1 row_mask:0xf bank_mask:0xf
	v_cndmask_b32_e64 v57, v18, v57, s[6:7]
	v_mov_b32_e32 v18, v19
	v_mov_b32_e32 v60, v19
	v_mov_b32_dpp v61, v34 row_shr:2 row_mask:0xf bank_mask:0xf
	v_mov_b32_dpp v18, v34 row_shr:1 row_mask:0xf bank_mask:0xf
	v_mov_b32_dpp v60, v218 row_shl:1 row_mask:0xf bank_mask:0xf
	v_cndmask_b32_e64 v60, v18, v60, s[6:7]
	v_cndmask_b32_e64 v62, v61, v218, s[4:5]
	v_mov_b32_e32 v18, v19
	v_mov_b32_e32 v61, v19
	v_mov_b32_e32 v59, v19
	v_mov_b32_dpp v18, v35 row_shr:1 row_mask:0xf bank_mask:0xf
	v_mov_b32_dpp v61, v219 row_shl:1 row_mask:0xf bank_mask:0xf
	v_mov_b32_dpp v59, v33 row_shr:2 row_mask:0xf bank_mask:0xf
	v_cndmask_b32_e64 v61, v18, v61, s[6:7]
	v_pk_fma_f32 v[32:33], v[32:33], v[88:89], v[92:93]
	v_mul_f32_e32 v18, 0xbfb8aa3b, v116
	v_pk_fma_f32 v[32:33], v[84:85], v[56:57], v[32:33]
	v_exp_f32_e32 v18, v18
	v_mul_f32_e32 v56, 0xbfb8aa3b, v117
	v_exp_f32_e32 v57, v56
	v_cndmask_b32_e64 v59, v59, v217, s[4:5]
	v_add_f32_e32 v18, 1.0, v18
	v_rcp_f32_e32 v56, v18
	v_add_f32_e32 v18, 1.0, v57
;     __device__ __forceinline__ f32x4 conv4s(const f32x4 c4, const f32x4 pv, int t, const f32x4 w0, const f32x4 w1, const f32x4 w2, const f32x4 bsv) const {
;         f32x4 p1, p2;
; #pragma unroll
;         for (int e = 0; e < 4; ++e) { p1[e] = dpp_f<0x111>(0.f, c4[e]); p2[e] = dpp_f<0x112>(0.f, c4[e]); const float q1 = dpp_f<0x101>(0.f, pv[e]);
;             p1[e] = t == 0 ? q1 : p1[e]; p2[e] = t < 2 ? pv[e] : p2[e]; }
;         f32x4 uu = bsv + w2 * c4 + w1 * p1 + w0 * p2;
;         asm volatile("" : "+v"(uu));
;     __device__ __forceinline__ void sample(f32x4 (&acc)[2][2][4][2], const Unit& u, int row0t, int wr, int wc, int fr, int fq) const {
;     ...
;         for (int step = 0; step < 4; ++step) {
;             const int n = (step == 1 || step == 2) ? 1 : 0, ai = step >> 1;
;             f32x4 w0, w1, w2, bsv;
;             if (step != 2) { const unsigned cso = (unsigned)((DFF + ca + 4 * n) * 4);
;                 w0 = *(const f32x4*)((const char*)cw + cso); w1 = *(const f32x4*)((const char*)(cw + DFF2) + cso); w2 = *(const f32x4*)((const char*)(cw + 2 * DFF2) + cso); bsv = *(const f32x4*)((const char*)cb + cso);
;                 wk[0] = w0; wk[1] = w1; wk[2] = w2; wk[3] = bsv; }
;             else { w0 = wk[0]; w1 = wk[1]; w2 = wk[2]; bsv = wk[3]; }
; #pragma unroll
;             for (int mp = 0; mp < 4; mp += 4) {
;             f32x4 pv[4];
; #pragma unroll
;             for (int k = 0; k < 4; ++k) { pv[k] = (f32x4){0.f, 0.f, 0.f, 0.f}; if (t < 2) pv[k] = *(const f32x4*)((const char*)st + stoff + (unsigned)(((16 * ai + 2 * (mp + k)) * 2 * DFF2 + DFF + 4 * n) * 4)); }
; #pragma unroll
;             for (int k = 0; k < 4; ++k) { const int m = mp + k;
;                 const f32x4 uu = conv4s(acc[ai][1][m][n], pv[k], t, w0, w1, w2, bsv);
;                 const f32x4 ua = acc[ai][0][m][n];
;                 u32x2 w; w.x = cvt_pk_bf16(silu_f(ua[0]) * uu[0], silu_f(ua[1]) * uu[1]); w.y = cvt_pk_bf16(silu_f(ua[2]) * uu[2], silu_f(ua[3]) * uu[3]);
;                 if ((step & 1) == 0) pend[m] = w;
;                 else { u32x4 o; if (n == 1) { o.x = pend[m].x; o.y = pend[m].y; o.z = w.x; o.w = w.y; } else { o.x = w.x; o.y = w.y; o.z = pend[m].x; o.w = pend[m].y; }
;                     *(u32x4*)((char*)act + rowoff0 + (unsigned)((ai * HALF + m * 16) * DFF * 2) + (unsigned)(ca * 2)) = o; }
;                 __builtin_amdgcn_sched_barrier(0);
	v_mul_f32_e32 v57, 0xbfb8aa3b, v118
	v_pk_fma_f32 v[32:33], v[68:69], v[58:59], v[32:33]
	v_exp_f32_e32 v58, v57
	v_mul_f32_e32 v57, 0xbfb8aa3b, v119
	v_exp_f32_e32 v59, v57
	v_mov_b32_e32 v63, v19
	v_rcp_f32_e32 v57, v18
	v_add_f32_e32 v18, 1.0, v58
	v_mov_b32_dpp v63, v35 row_shr:2 row_mask:0xf bank_mask:0xf
	v_pk_fma_f32 v[34:35], v[34:35], v[90:91], v[94:95]
	v_rcp_f32_e32 v58, v18
	v_add_f32_e32 v18, 1.0, v59
	v_cndmask_b32_e64 v63, v63, v219, s[4:5]
	v_pk_fma_f32 v[34:35], v[86:87], v[60:61], v[34:35]
	v_rcp_f32_e32 v59, v18
	v_pk_fma_f32 v[34:35], v[70:71], v[62:63], v[34:35]
	v_pk_mul_f32 v[56:57], v[116:117], v[56:57]
	s_nop 0
	v_pk_mul_f32 v[32:33], v[56:57], v[32:33]
	s_nop 0
	v_cvt_pk_bf16_f32 v104, v32, v33
	v_pk_mul_f32 v[32:33], v[118:119], v[58:59]
	s_nop 0
	v_pk_mul_f32 v[32:33], v[32:33], v[34:35]
	s_nop 0
	v_cvt_pk_bf16_f32 v105, v32, v33
	v_add_co_u32_e32 v32, vcc, 0x42000, v114
	s_nop 1
	v_addc_co_u32_e32 v33, vcc, 0, v115, vcc
	global_store_dwordx4 v[32:33], v[102:105], off
	v_mov_b32_e32 v56, 0
	v_mov_b32_e32 v64, 0
	v_mov_b32_e32 v65, 0
	v_mov_b32_e32 v66, 0
	v_mov_b32_e32 v67, 0
	v_mov_b32_e32 v57, 0
	v_mov_b32_e32 v58, 0
	v_mov_b32_e32 v59, 0
	v_mov_b32_e32 v32, 0
	v_mov_b32_e32 v60, 0
	v_mov_b32_e32 v61, 0
	v_mov_b32_e32 v62, 0
	v_mov_b32_e32 v63, 0
	v_mov_b32_e32 v33, 0
	v_mov_b32_e32 v34, 0
	v_mov_b32_e32 v35, 0
	v_mov_b32_e32 v18, v19
	v_mov_b32_e32 v101, v19
	v_mov_b32_e32 v100, v19
	v_mov_b32_dpp v18, v52 row_shr:1 row_mask:0xf bank_mask:0xf
	v_mov_b32_dpp v101, v52 row_shr:2 row_mask:0xf bank_mask:0xf
	s_waitcnt vmcnt(0)
	v_mov_b32_e32 v204, 0
	v_mov_b32_e32 v205, 0
	v_mov_b32_e32 v206, 0
	v_mov_b32_e32 v207, 0
	v_mov_b32_e32 v208, 0
	v_mov_b32_e32 v209, 0
	v_mov_b32_e32 v210, 0
	v_mov_b32_e32 v211, 0
	v_mov_b32_e32 v212, 0
	v_mov_b32_e32 v213, 0
	v_mov_b32_e32 v214, 0
	v_mov_b32_e32 v215, 0
	v_mov_b32_e32 v216, 0
	v_mov_b32_e32 v217, 0
	v_mov_b32_e32 v218, 0
	v_mov_b32_e32 v219, 0
	s_and_saveexec_b64 s[100:101], s[4:5]
	s_cbranch_execz .Lspp_7
	s_mov_b64 s[98:99], 0xb2c00
	v_lshl_add_u64 v[194:195], v[172:173], 0, s[98:99]
	global_load_dwordx4 v[204:207], v[194:195], off
	s_mov_b64 s[98:99], 0xc8c00
	v_lshl_add_u64 v[194:195], v[172:173], 0, s[98:99]
	global_load_dwordx4 v[208:211], v[194:195], off
	s_mov_b64 s[98:99], 0xdec00
	v_lshl_add_u64 v[194:195], v[172:173], 0, s[98:99]
	global_load_dwordx4 v[212:215], v[194:195], off
	s_mov_b64 s[98:99], 0xf4c00
	v_lshl_add_u64 v[194:195], v[172:173], 0, s[98:99]
	global_load_dwordx4 v[216:219], v[194:195], off
.Lspp_7:
	s_or_b64 exec, exec, s[100:101]
	s_nop 4
	v_mov_b32_dpp v100, v178 row_shl:1 row_mask:0xf bank_mask:0xf
	v_cndmask_b32_e64 v100, v18, v100, s[6:7]
	v_cndmask_b32_e64 v64, v101, v178, s[4:5]
	v_mov_b32_e32 v18, v19
	v_mov_b32_e32 v102, v19
	v_mov_b32_e32 v101, v19
	v_mov_b32_dpp v18, v53 row_shr:1 row_mask:0xf bank_mask:0xf
	v_mov_b32_dpp v102, v53 row_shr:2 row_mask:0xf bank_mask:0xf
	v_mov_b32_dpp v101, v179 row_shl:1 row_mask:0xf bank_mask:0xf
	v_cndmask_b32_e64 v101, v18, v101, s[6:7]
	v_cndmask_b32_e64 v65, v102, v179, s[4:5]
	v_mov_b32_e32 v18, v19
	v_mov_b32_e32 v103, v19
	v_mov_b32_e32 v102, v19
	v_mov_b32_dpp v18, v54 row_shr:1 row_mask:0xf bank_mask:0xf
	v_mov_b32_dpp v103, v54 row_shr:2 row_mask:0xf bank_mask:0xf
	v_mov_b32_dpp v102, v180 row_shl:1 row_mask:0xf bank_mask:0xf
	v_cndmask_b32_e64 v102, v18, v102, s[6:7]
	v_cndmask_b32_e64 v66, v103, v180, s[4:5]
	v_mov_b32_e32 v18, v19
	v_mov_b32_e32 v103, v19
	v_mov_b32_e32 v104, v19
	v_mov_b32_dpp v18, v55 row_shr:1 row_mask:0xf bank_mask:0xf
	v_mov_b32_dpp v103, v181 row_shl:1 row_mask:0xf bank_mask:0xf
	v_mov_b32_dpp v104, v55 row_shr:2 row_mask:0xf bank_mask:0xf
	v_cndmask_b32_e64 v103, v18, v103, s[6:7]
	v_pk_fma_f32 v[54:55], v[54:55], v[90:91], v[94:95]
	v_pk_fma_f32 v[52:53], v[52:53], v[88:89], v[92:93]
	v_cndmask_b32_e64 v67, v104, v181, s[4:5]
	v_pk_fma_f32 v[54:55], v[86:87], v[102:103], v[54:55]
	v_pk_fma_f32 v[52:53], v[84:85], v[100:101], v[52:53]
	v_mov_b32_e32 v171, v19
	v_pk_fma_f32 v[102:103], v[70:71], v[66:67], v[54:55]
	v_pk_fma_f32 v[100:101], v[68:69], v[64:65], v[52:53]
	v_lshl_add_u64 v[112:113], s[96:97], 0, v[170:171]
	v_lshl_add_u64 v[116:117], s[0:1], 0, v[170:171]
	v_lshl_add_u64 v[118:119], s[8:9], 0, v[170:171]
	v_lshl_add_u64 v[120:121], s[66:67], 0, v[170:171]
	v_mov_b32_e32 v18, v19
	v_mov_b32_e32 v53, v19
	v_mov_b32_e32 v52, v19
	v_mov_b32_dpp v18, v48 row_shr:1 row_mask:0xf bank_mask:0xf
	v_mov_b32_dpp v53, v48 row_shr:2 row_mask:0xf bank_mask:0xf
	v_mov_b32_dpp v52, v182 row_shl:1 row_mask:0xf bank_mask:0xf
	v_cndmask_b32_e64 v52, v18, v52, s[6:7]
	v_cndmask_b32_e64 v54, v53, v182, s[4:5]
	v_mov_b32_e32 v18, v19
	v_mov_b32_e32 v55, v19
	v_mov_b32_e32 v53, v19
	v_mov_b32_dpp v18, v49 row_shr:1 row_mask:0xf bank_mask:0xf
	v_mov_b32_dpp v55, v49 row_shr:2 row_mask:0xf bank_mask:0xf
	v_mov_b32_dpp v53, v183 row_shl:1 row_mask:0xf bank_mask:0xf
	v_cndmask_b32_e64 v53, v18, v53, s[6:7]
	v_cndmask_b32_e64 v55, v55, v183, s[4:5]
	v_mov_b32_e32 v18, v19
	v_mov_b32_e32 v57, v19
	v_mov_b32_e32 v56, v19
	v_mov_b32_dpp v18, v50 row_shr:1 row_mask:0xf bank_mask:0xf
	v_mov_b32_dpp v57, v50 row_shr:2 row_mask:0xf bank_mask:0xf
	v_mov_b32_dpp v56, v184 row_shl:1 row_mask:0xf bank_mask:0xf
	v_cndmask_b32_e64 v56, v18, v56, s[6:7]
	v_cndmask_b32_e64 v58, v57, v184, s[4:5]
	v_mov_b32_e32 v18, v19
	v_mov_b32_e32 v57, v19
	v_mov_b32_e32 v64, v19
	v_mov_b32_dpp v18, v51 row_shr:1 row_mask:0xf bank_mask:0xf
	v_mov_b32_dpp v57, v185 row_shl:1 row_mask:0xf bank_mask:0xf
	v_mov_b32_dpp v64, v51 row_shr:2 row_mask:0xf bank_mask:0xf
	v_cndmask_b32_e64 v57, v18, v57, s[6:7]
;     __device__ __forceinline__ f32x4 conv4s(const f32x4 c4, const f32x4 pv, int t, const f32x4 w0, const f32x4 w1, const f32x4 w2, const f32x4 bsv) const {
;         f32x4 p1, p2;
; #pragma unroll
;         for (int e = 0; e < 4; ++e) { p1[e] = dpp_f<0x111>(0.f, c4[e]); p2[e] = dpp_f<0x112>(0.f, c4[e]); const float q1 = dpp_f<0x101>(0.f, pv[e]);
;             p1[e] = t == 0 ? q1 : p1[e]; p2[e] = t < 2 ? pv[e] : p2[e]; }
;         f32x4 uu = bsv + w2 * c4 + w1 * p1 + w0 * p2;
;         asm volatile("" : "+v"(uu));
;     __device__ __forceinline__ void sample(f32x4 (&acc)[2][2][4][2], const Unit& u, int row0t, int wr, int wc, int fr, int fq) const {
;     ...
;         for (int step = 0; step < 4; ++step) {
;             const int n = (step == 1 || step == 2) ? 1 : 0, ai = step >> 1;
;             f32x4 w0, w1, w2, bsv;
;             if (step != 2) { const unsigned cso = (unsigned)((DFF + ca + 4 * n) * 4);
;                 w0 = *(const f32x4*)((const char*)cw + cso); w1 = *(const f32x4*)((const char*)(cw + DFF2) + cso); w2 = *(const f32x4*)((const char*)(cw + 2 * DFF2) + cso); bsv = *(const f32x4*)((const char*)cb + cso);
;                 wk[0] = w0; wk[1] = w1; wk[2] = w2; wk[3] = bsv; }
;             else { w0 = wk[0]; w1 = wk[1]; w2 = wk[2]; bsv = wk[3]; }
; #pragma unroll
;             for (int mp = 0; mp < 4; mp += 4) {
;             f32x4 pv[4];
; #pragma unroll
;             for (int k = 0; k < 4; ++k) { pv[k] = (f32x4){0.f, 0.f, 0.f, 0.f}; if (t < 2) pv[k] = *(const f32x4*)((const char*)st + stoff + (unsigned)(((16 * ai + 2 * (mp + k)) * 2 * DFF2 + DFF + 4 * n) * 4)); }
; #pragma unroll
;             for (int k = 0; k < 4; ++k) { const int m = mp + k;
;                 const f32x4 uu = conv4s(acc[ai][1][m][n], pv[k], t, w0, w1, w2, bsv);
;                 const f32x4 ua = acc[ai][0][m][n];
;                 u32x2 w; w.x = cvt_pk_bf16(silu_f(ua[0]) * uu[0], silu_f(ua[1]) * uu[1]); w.y = cvt_pk_bf16(silu_f(ua[2]) * uu[2], silu_f(ua[3]) * uu[3]);
;                 if ((step & 1) == 0) pend[m] = w;
;                 else { u32x4 o; if (n == 1) { o.x = pend[m].x; o.y = pend[m].y; o.z = w.x; o.w = w.y; } else { o.x = w.x; o.y = w.y; o.z = pend[m].x; o.w = pend[m].y; }
;                     *(u32x4*)((char*)act + rowoff0 + (unsigned)((ai * HALF + m * 16) * DFF * 2) + (unsigned)(ca * 2)) = o; }
;                 __builtin_amdgcn_sched_barrier(0);
	v_pk_fma_f32 v[50:51], v[50:51], v[90:91], v[94:95]
	v_pk_fma_f32 v[48:49], v[48:49], v[88:89], v[92:93]
	v_cndmask_b32_e64 v59, v64, v185, s[4:5]
	v_pk_fma_f32 v[50:51], v[86:87], v[56:57], v[50:51]
	v_pk_fma_f32 v[48:49], v[84:85], v[52:53], v[48:49]
	v_pk_fma_f32 v[106:107], v[70:71], v[58:59], v[50:51]
	v_pk_fma_f32 v[104:105], v[68:69], v[54:55], v[48:49]
	s_nop 0
	v_mov_b32_e32 v18, v19
	v_mov_b32_e32 v49, v19
	v_mov_b32_e32 v48, v19
	v_mov_b32_dpp v18, v44 row_shr:1 row_mask:0xf bank_mask:0xf
	v_mov_b32_dpp v49, v44 row_shr:2 row_mask:0xf bank_mask:0xf
	v_mov_b32_dpp v48, v186 row_shl:1 row_mask:0xf bank_mask:0xf
	v_cndmask_b32_e64 v48, v18, v48, s[6:7]
	v_cndmask_b32_e64 v50, v49, v186, s[4:5]
	v_mov_b32_e32 v18, v19
	v_mov_b32_e32 v49, v19
	v_mov_b32_e32 v53, v19
	v_mov_b32_dpp v18, v45 row_shr:1 row_mask:0xf bank_mask:0xf
	v_mov_b32_dpp v49, v187 row_shl:1 row_mask:0xf bank_mask:0xf
	v_cndmask_b32_e64 v49, v18, v49, s[6:7]
	v_mov_b32_e32 v18, v19
	v_mov_b32_e32 v52, v19
	v_mov_b32_dpp v53, v46 row_shr:2 row_mask:0xf bank_mask:0xf
	v_mov_b32_dpp v18, v46 row_shr:1 row_mask:0xf bank_mask:0xf
	v_mov_b32_dpp v52, v188 row_shl:1 row_mask:0xf bank_mask:0xf
	v_cndmask_b32_e64 v52, v18, v52, s[6:7]
	v_cndmask_b32_e64 v54, v53, v188, s[4:5]
	v_mov_b32_e32 v18, v19
	v_mov_b32_e32 v53, v19
	v_mov_b32_e32 v51, v19
	v_mov_b32_dpp v18, v47 row_shr:1 row_mask:0xf bank_mask:0xf
	v_mov_b32_e32 v55, v19
	v_mov_b32_dpp v53, v189 row_shl:1 row_mask:0xf bank_mask:0xf
	v_mov_b32_dpp v51, v45 row_shr:2 row_mask:0xf bank_mask:0xf
	v_mov_b32_dpp v55, v47 row_shr:2 row_mask:0xf bank_mask:0xf
	v_cndmask_b32_e64 v53, v18, v53, s[6:7]
	v_pk_fma_f32 v[46:47], v[46:47], v[90:91], v[94:95]
	v_pk_fma_f32 v[44:45], v[44:45], v[88:89], v[92:93]
	v_cndmask_b32_e64 v51, v51, v187, s[4:5]
	v_cndmask_b32_e64 v55, v55, v189, s[4:5]
	v_pk_fma_f32 v[46:47], v[86:87], v[52:53], v[46:47]
	v_pk_fma_f32 v[44:45], v[84:85], v[48:49], v[44:45]
	v_pk_fma_f32 v[110:111], v[70:71], v[54:55], v[46:47]
	v_pk_fma_f32 v[108:109], v[68:69], v[50:51], v[44:45]
	s_nop 0
	v_mov_b32_e32 v18, v19
	v_mov_b32_e32 v45, v19
	v_mov_b32_e32 v44, v19
	v_mov_b32_dpp v18, v20 row_shr:1 row_mask:0xf bank_mask:0xf
	v_mov_b32_dpp v45, v20 row_shr:2 row_mask:0xf bank_mask:0xf
	v_mov_b32_dpp v44, v190 row_shl:1 row_mask:0xf bank_mask:0xf
	v_cndmask_b32_e64 v44, v18, v44, s[6:7]
	v_cndmask_b32_e64 v32, v45, v190, s[4:5]
	v_mov_b32_e32 v18, v19
	v_mov_b32_e32 v46, v19
	v_mov_b32_e32 v45, v19
	v_mov_b32_dpp v18, v21 row_shr:1 row_mask:0xf bank_mask:0xf
	v_mov_b32_dpp v46, v21 row_shr:2 row_mask:0xf bank_mask:0xf
	v_mov_b32_dpp v45, v191 row_shl:1 row_mask:0xf bank_mask:0xf
	v_cndmask_b32_e64 v45, v18, v45, s[6:7]
	v_cndmask_b32_e64 v33, v46, v191, s[4:5]
	v_mov_b32_e32 v18, v19
	v_mov_b32_e32 v47, v19
	v_mov_b32_e32 v46, v19
	v_mov_b32_dpp v18, v22 row_shr:1 row_mask:0xf bank_mask:0xf
	v_mov_b32_dpp v47, v22 row_shr:2 row_mask:0xf bank_mask:0xf
	v_mov_b32_dpp v46, v192 row_shl:1 row_mask:0xf bank_mask:0xf
	v_cndmask_b32_e64 v46, v18, v46, s[6:7]
	v_cndmask_b32_e64 v34, v47, v192, s[4:5]
	v_mov_b32_e32 v18, v19
	v_mov_b32_e32 v47, v19
	v_mov_b32_e32 v48, v19
	v_mov_b32_dpp v18, v23 row_shr:1 row_mask:0xf bank_mask:0xf
	v_mov_b32_dpp v47, v193 row_shl:1 row_mask:0xf bank_mask:0xf
	v_mov_b32_dpp v48, v23 row_shr:2 row_mask:0xf bank_mask:0xf
	v_cndmask_b32_e64 v47, v18, v47, s[6:7]
	v_pk_fma_f32 v[22:23], v[22:23], v[90:91], v[94:95]
	v_pk_fma_f32 v[20:21], v[20:21], v[88:89], v[92:93]
	v_cndmask_b32_e64 v35, v48, v193, s[4:5]
	v_pk_fma_f32 v[22:23], v[86:87], v[46:47], v[22:23]
	v_pk_fma_f32 v[20:21], v[84:85], v[44:45], v[20:21]
	v_pk_fma_f32 v[86:87], v[70:71], v[34:35], v[22:23]
	v_pk_fma_f32 v[84:85], v[68:69], v[32:33], v[20:21]
	s_nop 0
	global_load_dwordx4 v[20:23], v[112:113], off
	global_load_dwordx4 v[32:35], v[116:117], off
	global_load_dwordx4 v[44:47], v[118:119], off
	global_load_dwordx4 v[48:51], v[120:121], off
	v_mov_b32_e32 v62, 0
	v_mov_b32_e32 v68, 0
	v_mov_b32_e32 v69, 0
	v_mov_b32_e32 v70, 0
	v_mov_b32_e32 v71, 0
	v_mov_b32_e32 v63, 0
	v_mov_b32_e32 v64, 0
	v_mov_b32_e32 v65, 0
	v_writelane_b32 v244, s50, 58
	s_nop 1
	v_writelane_b32 v244, s51, 59
	v_mov_b32_e32 v52, 0
	v_mov_b32_e32 v58, 0
	v_mov_b32_e32 v59, 0
	v_mov_b32_e32 v60, 0
	v_mov_b32_e32 v61, 0
	v_mov_b32_e32 v53, 0
	v_mov_b32_e32 v54, 0
	v_mov_b32_e32 v55, 0
	v_mul_f32_e32 v18, 0xbfb8aa3b, v96
	v_exp_f32_e32 v18, v18
	s_mov_b32 s0, 0xb0000
	v_add_f32_e32 v18, 1.0, v18
	v_rcp_f32_e32 v56, v18
	v_mul_f32_e32 v18, 0xbfb8aa3b, v97
	v_exp_f32_e32 v18, v18
	s_nop 0
	v_add_f32_e32 v18, 1.0, v18
	v_rcp_f32_e32 v57, v18
	v_mul_f32_e32 v18, 0xbfb8aa3b, v98
	v_exp_f32_e32 v18, v18
	v_pk_mul_f32 v[56:57], v[96:97], v[56:57]
	s_nop 0
	v_pk_mul_f32 v[56:57], v[56:57], v[84:85]
	v_add_f32_e32 v18, 1.0, v18
	v_rcp_f32_e32 v66, v18
	v_mul_f32_e32 v18, 0xbfb8aa3b, v99
	v_exp_f32_e32 v18, v18
	v_cvt_pk_bf16_f32 v56, v56, v57
	v_add_f32_e32 v18, 1.0, v18
	v_rcp_f32_e32 v67, v18
	v_mul_f32_e32 v18, 0xbfb8aa3b, v80
	v_exp_f32_e32 v18, v18
	v_pk_mul_f32 v[66:67], v[98:99], v[66:67]
	s_nop 0
	v_pk_mul_f32 v[66:67], v[66:67], v[86:87]
	v_add_f32_e32 v18, 1.0, v18
	v_cvt_pk_bf16_f32 v57, v66, v67
	v_rcp_f32_e32 v66, v18
	v_mul_f32_e32 v18, 0xbfb8aa3b, v81
	v_exp_f32_e32 v18, v18
	s_nop 0
	v_add_f32_e32 v18, 1.0, v18
	v_rcp_f32_e32 v67, v18
	v_mul_f32_e32 v18, 0xbfb8aa3b, v82
	v_exp_f32_e32 v18, v18
	v_pk_mul_f32 v[66:67], v[80:81], v[66:67]
	s_nop 0
	v_pk_mul_f32 v[66:67], v[66:67], v[108:109]
	v_add_f32_e32 v18, 1.0, v18
	v_rcp_f32_e32 v80, v18
	v_mul_f32_e32 v18, 0xbfb8aa3b, v83
	v_exp_f32_e32 v18, v18
	v_cvt_pk_bf16_f32 v66, v66, v67
;     __device__ __forceinline__ f32x4 conv4s(const f32x4 c4, const f32x4 pv, int t, const f32x4 w0, const f32x4 w1, const f32x4 w2, const f32x4 bsv) const {
;         f32x4 p1, p2;
; #pragma unroll
;         for (int e = 0; e < 4; ++e) { p1[e] = dpp_f<0x111>(0.f, c4[e]); p2[e] = dpp_f<0x112>(0.f, c4[e]); const float q1 = dpp_f<0x101>(0.f, pv[e]);
;             p1[e] = t == 0 ? q1 : p1[e]; p2[e] = t < 2 ? pv[e] : p2[e]; }
;         f32x4 uu = bsv + w2 * c4 + w1 * p1 + w0 * p2;
;         asm volatile("" : "+v"(uu));
;     __device__ __forceinline__ void sample(f32x4 (&acc)[2][2][4][2], const Unit& u, int row0t, int wr, int wc, int fr, int fq) const {
;     ...
;         for (int step = 0; step < 4; ++step) {
;             const int n = (step == 1 || step == 2) ? 1 : 0, ai = step >> 1;
;             f32x4 w0, w1, w2, bsv;
;             if (step != 2) { const unsigned cso = (unsigned)((DFF + ca + 4 * n) * 4);
;                 w0 = *(const f32x4*)((const char*)cw + cso); w1 = *(const f32x4*)((const char*)(cw + DFF2) + cso); w2 = *(const f32x4*)((const char*)(cw + 2 * DFF2) + cso); bsv = *(const f32x4*)((const char*)cb + cso);
;                 wk[0] = w0; wk[1] = w1; wk[2] = w2; wk[3] = bsv; }
;             else { w0 = wk[0]; w1 = wk[1]; w2 = wk[2]; bsv = wk[3]; }
; #pragma unroll
;             for (int mp = 0; mp < 4; mp += 4) {
;             f32x4 pv[4];
; #pragma unroll
;             for (int k = 0; k < 4; ++k) { pv[k] = (f32x4){0.f, 0.f, 0.f, 0.f}; if (t < 2) pv[k] = *(const f32x4*)((const char*)st + stoff + (unsigned)(((16 * ai + 2 * (mp + k)) * 2 * DFF2 + DFF + 4 * n) * 4)); }
; #pragma unroll
;             for (int k = 0; k < 4; ++k) { const int m = mp + k;
;                 const f32x4 uu = conv4s(acc[ai][1][m][n], pv[k], t, w0, w1, w2, bsv);
;                 const f32x4 ua = acc[ai][0][m][n];
;                 u32x2 w; w.x = cvt_pk_bf16(silu_f(ua[0]) * uu[0], silu_f(ua[1]) * uu[1]); w.y = cvt_pk_bf16(silu_f(ua[2]) * uu[2], silu_f(ua[3]) * uu[3]);
;                 if ((step & 1) == 0) pend[m] = w;
;                 else { u32x4 o; if (n == 1) { o.x = pend[m].x; o.y = pend[m].y; o.z = w.x; o.w = w.y; } else { o.x = w.x; o.y = w.y; o.z = pend[m].x; o.w = pend[m].y; }
;                     *(u32x4*)((char*)act + rowoff0 + (unsigned)((ai * HALF + m * 16) * DFF * 2) + (unsigned)(ca * 2)) = o; }
;                 __builtin_amdgcn_sched_barrier(0);
	v_add_f32_e32 v18, 1.0, v18
	v_rcp_f32_e32 v81, v18
	v_mul_f32_e32 v18, 0xbfb8aa3b, v76
	v_exp_f32_e32 v18, v18
	v_pk_mul_f32 v[80:81], v[82:83], v[80:81]
	s_nop 0
	v_pk_mul_f32 v[80:81], v[80:81], v[110:111]
	v_add_f32_e32 v18, 1.0, v18
	v_cvt_pk_bf16_f32 v67, v80, v81
	v_rcp_f32_e32 v80, v18
	v_mul_f32_e32 v18, 0xbfb8aa3b, v77
	v_exp_f32_e32 v18, v18
	s_nop 0
	v_add_f32_e32 v18, 1.0, v18
	v_rcp_f32_e32 v81, v18
	v_mul_f32_e32 v18, 0xbfb8aa3b, v78
	v_exp_f32_e32 v18, v18
	v_pk_mul_f32 v[76:77], v[76:77], v[80:81]
	s_nop 0
	v_pk_mul_f32 v[76:77], v[76:77], v[104:105]
	v_add_f32_e32 v18, 1.0, v18
	v_rcp_f32_e32 v80, v18
	v_mul_f32_e32 v18, 0xbfb8aa3b, v79
	v_exp_f32_e32 v18, v18
	v_cvt_pk_bf16_f32 v76, v76, v77
	v_add_f32_e32 v18, 1.0, v18
	v_rcp_f32_e32 v81, v18
	v_mul_f32_e32 v18, 0xbfb8aa3b, v72
	v_exp_f32_e32 v18, v18
	v_pk_mul_f32 v[78:79], v[78:79], v[80:81]
	s_nop 0
	v_pk_mul_f32 v[78:79], v[78:79], v[106:107]
	v_add_f32_e32 v18, 1.0, v18
	v_cvt_pk_bf16_f32 v77, v78, v79
	v_rcp_f32_e32 v78, v18
	v_mul_f32_e32 v18, 0xbfb8aa3b, v73
	v_exp_f32_e32 v18, v18
	v_mov_b32_e32 v80, v19
	v_add_f32_e32 v18, 1.0, v18
	v_rcp_f32_e32 v79, v18
	v_mul_f32_e32 v18, 0xbfb8aa3b, v74
	v_exp_f32_e32 v18, v18
	v_mov_b32_dpp v80, v17 row_shr:2 row_mask:0xf bank_mask:0xf
	v_pk_mul_f32 v[72:73], v[72:73], v[78:79]
	v_add_f32_e32 v18, 1.0, v18
	v_rcp_f32_e32 v78, v18
	v_mul_f32_e32 v18, 0xbfb8aa3b, v75
	v_exp_f32_e32 v18, v18
	v_pk_mul_f32 v[72:73], v[72:73], v[100:101]
	v_add_f32_e32 v18, 1.0, v18
	v_rcp_f32_e32 v79, v18
	v_cvt_pk_bf16_f32 v72, v72, v73
	v_mov_b32_e32 v18, v19
	v_pk_mul_f32 v[74:75], v[74:75], v[78:79]
	s_nop 0
	v_pk_mul_f32 v[74:75], v[74:75], v[102:103]
	v_mov_b32_dpp v18, v14 row_shr:1 row_mask:0xf bank_mask:0xf
	v_cvt_pk_bf16_f32 v73, v74, v75
	v_mov_b32_e32 v75, v19
	v_mov_b32_e32 v74, v19
	v_mov_b32_e32 v78, v19
	v_mov_b32_dpp v75, v14 row_shr:2 row_mask:0xf bank_mask:0xf
	s_waitcnt vmcnt(0)
	v_mov_b32_dpp v74, v204 row_shl:1 row_mask:0xf bank_mask:0xf
	v_cndmask_b32_e64 v74, v18, v74, s[6:7]
	v_cndmask_b32_e64 v68, v75, v204, s[4:5]
	v_mov_b32_e32 v18, v19
	v_mov_b32_e32 v75, v19
	v_mov_b32_dpp v78, v15 row_shr:2 row_mask:0xf bank_mask:0xf
	v_mov_b32_dpp v18, v15 row_shr:1 row_mask:0xf bank_mask:0xf
	v_mov_b32_dpp v75, v205 row_shl:1 row_mask:0xf bank_mask:0xf
	v_cndmask_b32_e64 v75, v18, v75, s[6:7]
	v_cndmask_b32_e64 v69, v78, v205, s[4:5]
	v_mov_b32_e32 v18, v19
	v_mov_b32_e32 v79, v19
	v_mov_b32_e32 v78, v19
	v_mov_b32_dpp v18, v16 row_shr:1 row_mask:0xf bank_mask:0xf
	v_mov_b32_dpp v79, v16 row_shr:2 row_mask:0xf bank_mask:0xf
	v_mov_b32_dpp v78, v206 row_shl:1 row_mask:0xf bank_mask:0xf
	v_cndmask_b32_e64 v78, v18, v78, s[6:7]
	v_cndmask_b32_e64 v70, v79, v206, s[4:5]
	v_mov_b32_e32 v18, v19
	v_mov_b32_e32 v79, v19
	v_pk_fma_f32 v[14:15], v[14:15], v[44:45], v[48:49]
	v_mov_b32_dpp v18, v17 row_shr:1 row_mask:0xf bank_mask:0xf
	v_mov_b32_dpp v79, v207 row_shl:1 row_mask:0xf bank_mask:0xf
	v_cndmask_b32_e64 v79, v18, v79, s[6:7]
	v_mul_f32_e32 v18, 0xbfb8aa3b, v40
	v_exp_f32_e32 v18, v18
	v_pk_fma_f32 v[14:15], v[32:33], v[74:75], v[14:15]
	v_pk_fma_f32 v[16:17], v[16:17], v[46:47], v[50:51]
	v_pk_fma_f32 v[14:15], v[20:21], v[68:69], v[14:15]
	v_add_f32_e32 v18, 1.0, v18
	v_rcp_f32_e32 v68, v18
	v_mul_f32_e32 v18, 0xbfb8aa3b, v41
	v_exp_f32_e32 v18, v18
	v_cndmask_b32_e64 v71, v80, v207, s[4:5]
	v_pk_fma_f32 v[16:17], v[34:35], v[78:79], v[16:17]
	v_add_f32_e32 v18, 1.0, v18
	v_rcp_f32_e32 v69, v18
	v_pk_fma_f32 v[16:17], v[22:23], v[70:71], v[16:17]
	v_pk_mul_f32 v[40:41], v[40:41], v[68:69]
	s_nop 0
	v_pk_mul_f32 v[14:15], v[40:41], v[14:15]
	s_nop 0
	v_cvt_pk_bf16_f32 v70, v14, v15
	v_mul_f32_e32 v14, 0xbfb8aa3b, v42
	v_mul_f32_e32 v15, 0xbfb8aa3b, v43
	v_exp_f32_e32 v14, v14
	v_exp_f32_e32 v15, v15
	v_add_f32_e32 v14, 1.0, v14
	v_add_f32_e32 v15, 1.0, v15
	v_rcp_f32_e32 v14, v14
	v_rcp_f32_e32 v15, v15
	s_nop 0
	v_pk_mul_f32 v[14:15], v[42:43], v[14:15]
	s_nop 0
	v_pk_mul_f32 v[14:15], v[14:15], v[16:17]
	s_nop 0
	v_cvt_pk_bf16_f32 v71, v14, v15
	v_add_co_u32_e32 v14, vcc, s0, v114
	s_nop 1
	v_addc_co_u32_e32 v15, vcc, 0, v115, vcc
	global_store_dwordx4 v[14:15], v[70:73], off
	v_mov_b32_e32 v14, v19
	v_mov_b32_e32 v15, v19
	v_mov_b32_e32 v16, v19
	v_mov_b32_dpp v14, v10 row_shr:1 row_mask:0xf bank_mask:0xf
	v_mov_b32_dpp v15, v10 row_shr:2 row_mask:0xf bank_mask:0xf
	v_mov_b32_dpp v16, v208 row_shl:1 row_mask:0xf bank_mask:0xf
	v_cndmask_b32_e64 v14, v14, v16, s[6:7]
	v_cndmask_b32_e64 v16, v15, v208, s[4:5]
	v_mov_b32_e32 v15, v19
	v_mov_b32_e32 v18, v19
	v_mov_b32_e32 v17, v19
	v_mov_b32_dpp v15, v11 row_shr:1 row_mask:0xf bank_mask:0xf
	v_mov_b32_dpp v18, v209 row_shl:1 row_mask:0xf bank_mask:0xf
	v_mov_b32_dpp v17, v11 row_shr:2 row_mask:0xf bank_mask:0xf
	v_cndmask_b32_e64 v15, v15, v18, s[6:7]
	v_pk_fma_f32 v[10:11], v[10:11], v[44:45], v[48:49]
	v_cndmask_b32_e64 v17, v17, v209, s[4:5]
	v_pk_fma_f32 v[10:11], v[32:33], v[14:15], v[10:11]
	v_mul_f32_e32 v14, 0xbfb8aa3b, v36
	v_mul_f32_e32 v15, 0xbfb8aa3b, v37
	v_exp_f32_e32 v14, v14
	v_exp_f32_e32 v15, v15
	v_pk_fma_f32 v[10:11], v[20:21], v[16:17], v[10:11]
	v_mul_f32_e32 v16, 0xbfb8aa3b, v38
	v_mul_f32_e32 v17, 0xbfb8aa3b, v39
	v_mov_b32_e32 v18, v19
	v_mov_b32_e32 v41, v19
	v_mov_b32_e32 v40, v19
	v_exp_f32_e32 v16, v16
	v_exp_f32_e32 v17, v17
	v_mov_b32_dpp v18, v12 row_shr:1 row_mask:0xf bank_mask:0xf
	v_mov_b32_dpp v41, v12 row_shr:2 row_mask:0xf bank_mask:0xf
	v_mov_b32_dpp v40, v210 row_shl:1 row_mask:0xf bank_mask:0xf
	v_cndmask_b32_e64 v40, v18, v40, s[6:7]
	v_cndmask_b32_e64 v42, v41, v210, s[4:5]
	v_mov_b32_e32 v18, v19
	v_mov_b32_e32 v41, v19
;     __device__ __forceinline__ f32x4 conv4s(const f32x4 c4, const f32x4 pv, int t, const f32x4 w0, const f32x4 w1, const f32x4 w2, const f32x4 bsv) const {
;         f32x4 p1, p2;
; #pragma unroll
;         for (int e = 0; e < 4; ++e) { p1[e] = dpp_f<0x111>(0.f, c4[e]); p2[e] = dpp_f<0x112>(0.f, c4[e]); const float q1 = dpp_f<0x101>(0.f, pv[e]);
;             p1[e] = t == 0 ? q1 : p1[e]; p2[e] = t < 2 ? pv[e] : p2[e]; }
;         f32x4 uu = bsv + w2 * c4 + w1 * p1 + w0 * p2;
;         asm volatile("" : "+v"(uu));
;     __device__ __forceinline__ void sample(f32x4 (&acc)[2][2][4][2], const Unit& u, int row0t, int wr, int wc, int fr, int fq) const {
;     ...
;         for (int step = 0; step < 4; ++step) {
;             const int n = (step == 1 || step == 2) ? 1 : 0, ai = step >> 1;
;             f32x4 w0, w1, w2, bsv;
;             if (step != 2) { const unsigned cso = (unsigned)((DFF + ca + 4 * n) * 4);
;                 w0 = *(const f32x4*)((const char*)cw + cso); w1 = *(const f32x4*)((const char*)(cw + DFF2) + cso); w2 = *(const f32x4*)((const char*)(cw + 2 * DFF2) + cso); bsv = *(const f32x4*)((const char*)cb + cso);
;                 wk[0] = w0; wk[1] = w1; wk[2] = w2; wk[3] = bsv; }
;             else { w0 = wk[0]; w1 = wk[1]; w2 = wk[2]; bsv = wk[3]; }
; #pragma unroll
;             for (int mp = 0; mp < 4; mp += 4) {
;             f32x4 pv[4];
; #pragma unroll
;             for (int k = 0; k < 4; ++k) { pv[k] = (f32x4){0.f, 0.f, 0.f, 0.f}; if (t < 2) pv[k] = *(const f32x4*)((const char*)st + stoff + (unsigned)(((16 * ai + 2 * (mp + k)) * 2 * DFF2 + DFF + 4 * n) * 4)); }
; #pragma unroll
;             for (int k = 0; k < 4; ++k) { const int m = mp + k;
;                 const f32x4 uu = conv4s(acc[ai][1][m][n], pv[k], t, w0, w1, w2, bsv);
;                 const f32x4 ua = acc[ai][0][m][n];
;                 u32x2 w; w.x = cvt_pk_bf16(silu_f(ua[0]) * uu[0], silu_f(ua[1]) * uu[1]); w.y = cvt_pk_bf16(silu_f(ua[2]) * uu[2], silu_f(ua[3]) * uu[3]);
;                 if ((step & 1) == 0) pend[m] = w;
;                 else { u32x4 o; if (n == 1) { o.x = pend[m].x; o.y = pend[m].y; o.z = w.x; o.w = w.y; } else { o.x = w.x; o.y = w.y; o.z = pend[m].x; o.w = pend[m].y; }
;                     *(u32x4*)((char*)act + rowoff0 + (unsigned)((ai * HALF + m * 16) * DFF * 2) + (unsigned)(ca * 2)) = o; }
;                 __builtin_amdgcn_sched_barrier(0);
	v_add_f32_e32 v14, 1.0, v14
	v_add_f32_e32 v15, 1.0, v15
	v_mov_b32_dpp v18, v13 row_shr:1 row_mask:0xf bank_mask:0xf
	v_mov_b32_e32 v43, v19
	v_mov_b32_dpp v41, v211 row_shl:1 row_mask:0xf bank_mask:0xf
	v_rcp_f32_e32 v14, v14
	v_rcp_f32_e32 v15, v15
	v_mov_b32_dpp v43, v13 row_shr:2 row_mask:0xf bank_mask:0xf
	v_cndmask_b32_e64 v41, v18, v41, s[6:7]
	v_pk_fma_f32 v[12:13], v[12:13], v[46:47], v[50:51]
	v_add_f32_e32 v16, 1.0, v16
	v_add_f32_e32 v17, 1.0, v17
	v_cndmask_b32_e64 v43, v43, v211, s[4:5]
	v_pk_fma_f32 v[12:13], v[34:35], v[40:41], v[12:13]
	v_rcp_f32_e32 v16, v16
	v_rcp_f32_e32 v17, v17
	v_pk_fma_f32 v[12:13], v[22:23], v[42:43], v[12:13]
	v_pk_mul_f32 v[14:15], v[36:37], v[14:15]
	s_mov_b32 s0, 0xc6000
	v_pk_mul_f32 v[10:11], v[14:15], v[10:11]
	s_nop 0
	v_cvt_pk_bf16_f32 v74, v10, v11
	v_pk_mul_f32 v[10:11], v[38:39], v[16:17]
	s_nop 0
	v_pk_mul_f32 v[10:11], v[10:11], v[12:13]
	s_nop 0
	v_cvt_pk_bf16_f32 v75, v10, v11
	v_add_co_u32_e32 v10, vcc, s0, v114
	s_nop 1
	v_addc_co_u32_e32 v11, vcc, 0, v115, vcc
	global_store_dwordx4 v[10:11], v[74:77], off
	v_mov_b32_e32 v10, v19
	v_mov_b32_e32 v11, v19
	v_mov_b32_e32 v12, v19
	v_mov_b32_dpp v10, v6 row_shr:1 row_mask:0xf bank_mask:0xf
	v_mov_b32_dpp v11, v6 row_shr:2 row_mask:0xf bank_mask:0xf
	v_mov_b32_dpp v12, v212 row_shl:1 row_mask:0xf bank_mask:0xf
	v_cndmask_b32_e64 v10, v10, v12, s[6:7]
	v_cndmask_b32_e64 v12, v11, v212, s[4:5]
	v_mov_b32_e32 v11, v19
	v_mov_b32_e32 v14, v19
	v_mov_b32_e32 v13, v19
	v_mov_b32_dpp v11, v7 row_shr:1 row_mask:0xf bank_mask:0xf
	v_mov_b32_dpp v14, v213 row_shl:1 row_mask:0xf bank_mask:0xf
	v_mov_b32_dpp v13, v7 row_shr:2 row_mask:0xf bank_mask:0xf
	v_cndmask_b32_e64 v11, v11, v14, s[6:7]
	v_pk_fma_f32 v[6:7], v[6:7], v[44:45], v[48:49]
	v_cndmask_b32_e64 v13, v13, v213, s[4:5]
	v_pk_fma_f32 v[6:7], v[32:33], v[10:11], v[6:7]
	v_mul_f32_e32 v10, 0xbfb8aa3b, v28
	v_mul_f32_e32 v11, 0xbfb8aa3b, v29
	v_exp_f32_e32 v10, v10
	v_exp_f32_e32 v11, v11
	v_pk_fma_f32 v[6:7], v[20:21], v[12:13], v[6:7]
	v_mul_f32_e32 v12, 0xbfb8aa3b, v30
	v_mul_f32_e32 v13, 0xbfb8aa3b, v31
	v_mov_b32_e32 v14, v19
	v_mov_b32_e32 v15, v19
	v_mov_b32_e32 v16, v19
	v_exp_f32_e32 v12, v12
	v_exp_f32_e32 v13, v13
	v_mov_b32_dpp v14, v8 row_shr:1 row_mask:0xf bank_mask:0xf
	v_mov_b32_dpp v15, v8 row_shr:2 row_mask:0xf bank_mask:0xf
	v_mov_b32_dpp v16, v214 row_shl:1 row_mask:0xf bank_mask:0xf
	v_cndmask_b32_e64 v14, v14, v16, s[6:7]
	v_cndmask_b32_e64 v16, v15, v214, s[4:5]
	v_mov_b32_e32 v15, v19
	v_mov_b32_e32 v18, v19
	v_add_f32_e32 v10, 1.0, v10
	v_add_f32_e32 v11, 1.0, v11
	v_mov_b32_dpp v15, v9 row_shr:1 row_mask:0xf bank_mask:0xf
	v_mov_b32_e32 v17, v19
	v_mov_b32_dpp v18, v215 row_shl:1 row_mask:0xf bank_mask:0xf
	v_rcp_f32_e32 v10, v10
	v_rcp_f32_e32 v11, v11
	v_mov_b32_dpp v17, v9 row_shr:2 row_mask:0xf bank_mask:0xf
	v_cndmask_b32_e64 v15, v15, v18, s[6:7]
	v_pk_fma_f32 v[8:9], v[8:9], v[46:47], v[50:51]
	v_add_f32_e32 v12, 1.0, v12
	v_add_f32_e32 v13, 1.0, v13
	v_cndmask_b32_e64 v17, v17, v215, s[4:5]
	v_pk_fma_f32 v[8:9], v[34:35], v[14:15], v[8:9]
	v_rcp_f32_e32 v12, v12
	v_rcp_f32_e32 v13, v13
	v_pk_fma_f32 v[8:9], v[22:23], v[16:17], v[8:9]
	v_pk_mul_f32 v[10:11], v[28:29], v[10:11]
	s_mov_b32 s0, 0xdc000
	v_pk_mul_f32 v[6:7], v[10:11], v[6:7]
	s_nop 0
	v_cvt_pk_bf16_f32 v64, v6, v7
	v_pk_mul_f32 v[6:7], v[30:31], v[12:13]
	s_nop 0
	v_pk_mul_f32 v[6:7], v[6:7], v[8:9]
	s_nop 0
	v_cvt_pk_bf16_f32 v65, v6, v7
	v_add_co_u32_e32 v6, vcc, s0, v114
	s_nop 1
	v_addc_co_u32_e32 v7, vcc, 0, v115, vcc
	global_store_dwordx4 v[6:7], v[64:67], off
	v_mov_b32_e32 v6, v19
	v_mov_b32_e32 v7, v19
	v_mov_b32_e32 v8, v19
	v_mov_b32_dpp v6, v2 row_shr:1 row_mask:0xf bank_mask:0xf
	v_mov_b32_dpp v7, v2 row_shr:2 row_mask:0xf bank_mask:0xf
	v_mov_b32_dpp v8, v216 row_shl:1 row_mask:0xf bank_mask:0xf
	v_cndmask_b32_e64 v6, v6, v8, s[6:7]
	v_cndmask_b32_e64 v8, v7, v216, s[4:5]
	v_mov_b32_e32 v7, v19
	v_mov_b32_e32 v10, v19
	v_mov_b32_e32 v9, v19
	v_mov_b32_dpp v7, v3 row_shr:1 row_mask:0xf bank_mask:0xf
	v_mov_b32_dpp v10, v217 row_shl:1 row_mask:0xf bank_mask:0xf
	v_mov_b32_dpp v9, v3 row_shr:2 row_mask:0xf bank_mask:0xf
	v_cndmask_b32_e64 v7, v7, v10, s[6:7]
	v_pk_fma_f32 v[2:3], v[2:3], v[44:45], v[48:49]
	v_cndmask_b32_e64 v9, v9, v217, s[4:5]
	v_pk_fma_f32 v[2:3], v[32:33], v[6:7], v[2:3]
	v_mul_f32_e32 v6, 0xbfb8aa3b, v24
	v_mul_f32_e32 v7, 0xbfb8aa3b, v25
	v_exp_f32_e32 v6, v6
	v_exp_f32_e32 v7, v7
	v_pk_fma_f32 v[2:3], v[20:21], v[8:9], v[2:3]
	v_mul_f32_e32 v8, 0xbfb8aa3b, v26
	v_mul_f32_e32 v9, 0xbfb8aa3b, v27
	v_mov_b32_e32 v10, v19
	v_mov_b32_e32 v11, v19
	v_mov_b32_e32 v12, v19
	v_exp_f32_e32 v8, v8
	v_exp_f32_e32 v9, v9
	v_mov_b32_dpp v10, v4 row_shr:1 row_mask:0xf bank_mask:0xf
	v_mov_b32_dpp v11, v4 row_shr:2 row_mask:0xf bank_mask:0xf
	v_mov_b32_dpp v12, v218 row_shl:1 row_mask:0xf bank_mask:0xf
	v_cndmask_b32_e64 v10, v10, v12, s[6:7]
	v_cndmask_b32_e64 v12, v11, v218, s[4:5]
	v_mov_b32_e32 v11, v19
	v_mov_b32_e32 v14, v19
	v_add_f32_e32 v6, 1.0, v6
	v_add_f32_e32 v7, 1.0, v7
	v_mov_b32_dpp v11, v5 row_shr:1 row_mask:0xf bank_mask:0xf
	v_mov_b32_e32 v13, v19
	v_mov_b32_dpp v14, v219 row_shl:1 row_mask:0xf bank_mask:0xf
	v_rcp_f32_e32 v6, v6
	v_rcp_f32_e32 v7, v7
	v_mov_b32_dpp v13, v5 row_shr:2 row_mask:0xf bank_mask:0xf
	v_cndmask_b32_e64 v11, v11, v14, s[6:7]
	v_pk_fma_f32 v[4:5], v[4:5], v[46:47], v[50:51]
	v_add_f32_e32 v8, 1.0, v8
	v_add_f32_e32 v9, 1.0, v9
	v_cndmask_b32_e64 v13, v13, v219, s[4:5]
	v_pk_fma_f32 v[4:5], v[34:35], v[10:11], v[4:5]
	v_rcp_f32_e32 v8, v8
	v_rcp_f32_e32 v9, v9
	v_pk_fma_f32 v[4:5], v[22:23], v[12:13], v[4:5]
	v_pk_mul_f32 v[6:7], v[24:25], v[6:7]
	s_nop 0
	v_pk_mul_f32 v[2:3], v[6:7], v[2:3]
	s_nop 0
	v_cvt_pk_bf16_f32 v54, v2, v3
	v_pk_mul_f32 v[2:3], v[26:27], v[8:9]
	s_nop 0
	v_pk_mul_f32 v[2:3], v[2:3], v[4:5]
	s_nop 0
	v_cvt_pk_bf16_f32 v55, v2, v3
	v_add_co_u32_e32 v2, vcc, 0xf2000, v114
	s_nop 1
	v_addc_co_u32_e32 v3, vcc, 0, v115, vcc
	global_store_dwordx4 v[2:3], v[54:57], off
	s_waitcnt vmcnt(0)
	s_barrier
